# same as previous best but every wait before consuming hoisted epilogue loads counts younger loads only, so it holds whether or not stores retire in order with loads
# speedup vs baseline: 1.0043x; 1.0043x over previous
.LBB0_710:
	v_add_u32_e32 v70, 0, v24
	v_add_u32_e32 v74, 0xffffbf80, v70
	v_ashrrev_i32_e32 v71, 31, v70
	v_cmp_gt_i32_e32 vcc, s35, v70
	v_mov_b32_e32 v65, s12
	v_mov_b32_e32 v76, s33
	v_mov_b32_e32 v78, s11
	v_mov_b32_e32 v79, s13
	v_mov_b64_e32 v[72:73], s[30:31]
	v_cndmask_b32_e32 v75, 0, v71, vcc
	v_cndmask_b32_e32 v74, v74, v70, vcc
	v_mad_i64_i32 v[72:73], s[50:51], v70, s40, v[72:73]
	v_cndmask_b32_e32 v77, v65, v76, vcc
	v_cndmask_b32_e32 v76, v78, v79, vcc
	v_lshlrev_b64 v[78:79], 6, v[70:71]
	v_lshlrev_b64 v[70:71], 11, v[70:71]
	v_lshlrev_b64 v[74:75], 11, v[74:75]
	v_lshl_add_u64 v[72:73], v[72:73], 0, v[30:31]
	v_lshl_add_u64 v[70:71], v[76:77], 0, v[74:75]
	v_add_co_u32_e32 v80, vcc, s41, v72
	v_lshl_add_u64 v[78:79], v[26:27], 0, v[78:79]
	v_lshl_add_u64 v[70:71], v[70:71], 0, v[30:31]
	v_addc_co_u32_e32 v81, vcc, 0, v73, vcc
	global_load_dwordx4 v[100:103], v[70:71], off
	s_nop 0
	global_load_dwordx4 v[104:107], v[80:81], off
	s_nop 0
	global_load_dword v240, v[78:79], off
	v_add_u32_e32 v70, 16, v24
	v_add_u32_e32 v74, 0xffffbf80, v70
	v_ashrrev_i32_e32 v71, 31, v70
	v_cmp_gt_i32_e32 vcc, s35, v70
	v_mov_b32_e32 v65, s12
	v_mov_b32_e32 v76, s33
	v_mov_b32_e32 v78, s11
	v_mov_b32_e32 v79, s13
	v_mov_b64_e32 v[72:73], s[30:31]
	v_cndmask_b32_e32 v75, 0, v71, vcc
	v_cndmask_b32_e32 v74, v74, v70, vcc
	v_mad_i64_i32 v[72:73], s[50:51], v70, s40, v[72:73]
	v_cndmask_b32_e32 v77, v65, v76, vcc
	v_cndmask_b32_e32 v76, v78, v79, vcc
	v_lshlrev_b64 v[78:79], 6, v[70:71]
	v_lshlrev_b64 v[70:71], 11, v[70:71]
	v_lshlrev_b64 v[74:75], 11, v[74:75]
	v_lshl_add_u64 v[72:73], v[72:73], 0, v[30:31]
	v_lshl_add_u64 v[70:71], v[76:77], 0, v[74:75]
	v_add_co_u32_e32 v80, vcc, s41, v72
	v_lshl_add_u64 v[78:79], v[26:27], 0, v[78:79]
	v_lshl_add_u64 v[70:71], v[70:71], 0, v[30:31]
	v_addc_co_u32_e32 v81, vcc, 0, v73, vcc
	global_load_dwordx4 v[108:111], v[70:71], off
	s_nop 0
	global_load_dwordx4 v[112:115], v[80:81], off
	s_nop 0
	global_load_dword v241, v[78:79], off
	v_add_u32_e32 v70, 32, v24
	v_add_u32_e32 v74, 0xffffbf80, v70
	v_ashrrev_i32_e32 v71, 31, v70
	v_cmp_gt_i32_e32 vcc, s35, v70
	v_mov_b32_e32 v65, s12
	v_mov_b32_e32 v76, s33
	v_mov_b32_e32 v78, s11
	v_mov_b32_e32 v79, s13
	v_mov_b64_e32 v[72:73], s[30:31]
	v_cndmask_b32_e32 v75, 0, v71, vcc
	v_cndmask_b32_e32 v74, v74, v70, vcc
	v_mad_i64_i32 v[72:73], s[50:51], v70, s40, v[72:73]
	v_cndmask_b32_e32 v77, v65, v76, vcc
	v_cndmask_b32_e32 v76, v78, v79, vcc
	v_lshlrev_b64 v[78:79], 6, v[70:71]
	v_lshlrev_b64 v[70:71], 11, v[70:71]
	v_lshlrev_b64 v[74:75], 11, v[74:75]
	v_lshl_add_u64 v[72:73], v[72:73], 0, v[30:31]
	v_lshl_add_u64 v[70:71], v[76:77], 0, v[74:75]
	v_add_co_u32_e32 v80, vcc, s41, v72
	v_lshl_add_u64 v[78:79], v[26:27], 0, v[78:79]
	v_lshl_add_u64 v[70:71], v[70:71], 0, v[30:31]
	v_addc_co_u32_e32 v81, vcc, 0, v73, vcc
	global_load_dwordx4 v[116:119], v[70:71], off
	s_nop 0
	global_load_dwordx4 v[120:123], v[80:81], off
	s_nop 0
	global_load_dword v242, v[78:79], off
	v_add_u32_e32 v70, 48, v24
	v_add_u32_e32 v74, 0xffffbf80, v70
	v_ashrrev_i32_e32 v71, 31, v70
	v_cmp_gt_i32_e32 vcc, s35, v70
	v_mov_b32_e32 v65, s12
	v_mov_b32_e32 v76, s33
	v_mov_b32_e32 v78, s11
	v_mov_b32_e32 v79, s13
	v_mov_b64_e32 v[72:73], s[30:31]
	v_cndmask_b32_e32 v75, 0, v71, vcc
	v_cndmask_b32_e32 v74, v74, v70, vcc
	v_mad_i64_i32 v[72:73], s[50:51], v70, s40, v[72:73]
	v_cndmask_b32_e32 v77, v65, v76, vcc
	v_cndmask_b32_e32 v76, v78, v79, vcc
	v_lshlrev_b64 v[78:79], 6, v[70:71]
	v_lshlrev_b64 v[70:71], 11, v[70:71]
	v_lshlrev_b64 v[74:75], 11, v[74:75]
	v_lshl_add_u64 v[72:73], v[72:73], 0, v[30:31]
	v_lshl_add_u64 v[70:71], v[76:77], 0, v[74:75]
	v_add_co_u32_e32 v80, vcc, s41, v72
	v_lshl_add_u64 v[78:79], v[26:27], 0, v[78:79]
	v_lshl_add_u64 v[70:71], v[70:71], 0, v[30:31]
	v_addc_co_u32_e32 v81, vcc, 0, v73, vcc
	global_load_dwordx4 v[124:127], v[70:71], off
	s_nop 0
	global_load_dwordx4 v[130:133], v[80:81], off
	s_nop 0
	global_load_dword v243, v[78:79], off
	v_add_u32_e32 v70, 64, v24
	v_add_u32_e32 v74, 0xffffbf80, v70
	v_ashrrev_i32_e32 v71, 31, v70
	v_cmp_gt_i32_e32 vcc, s35, v70
	v_mov_b32_e32 v65, s12
	v_mov_b32_e32 v76, s33
	v_mov_b32_e32 v78, s11
	v_mov_b32_e32 v79, s13
	v_mov_b64_e32 v[72:73], s[30:31]
	v_cndmask_b32_e32 v75, 0, v71, vcc
	v_cndmask_b32_e32 v74, v74, v70, vcc
	v_mad_i64_i32 v[72:73], s[50:51], v70, s40, v[72:73]
	v_cndmask_b32_e32 v77, v65, v76, vcc
	v_cndmask_b32_e32 v76, v78, v79, vcc
	v_lshlrev_b64 v[78:79], 6, v[70:71]
	v_lshlrev_b64 v[70:71], 11, v[70:71]
	v_lshlrev_b64 v[74:75], 11, v[74:75]
	v_lshl_add_u64 v[72:73], v[72:73], 0, v[30:31]
	v_lshl_add_u64 v[70:71], v[76:77], 0, v[74:75]
	v_add_co_u32_e32 v80, vcc, s41, v72
	v_lshl_add_u64 v[78:79], v[26:27], 0, v[78:79]
	v_lshl_add_u64 v[70:71], v[70:71], 0, v[30:31]
	v_addc_co_u32_e32 v81, vcc, 0, v73, vcc
	global_load_dwordx4 v[134:137], v[70:71], off
	s_nop 0
	global_load_dwordx4 v[138:141], v[80:81], off
	s_nop 0
	global_load_dword v244, v[78:79], off
	v_add_u32_e32 v70, 80, v24
	v_add_u32_e32 v74, 0xffffbf80, v70
	v_ashrrev_i32_e32 v71, 31, v70
	v_cmp_gt_i32_e32 vcc, s35, v70
	v_mov_b32_e32 v65, s12
	v_mov_b32_e32 v76, s33
	v_mov_b32_e32 v78, s11
	v_mov_b32_e32 v79, s13
	v_mov_b64_e32 v[72:73], s[30:31]
	v_cndmask_b32_e32 v75, 0, v71, vcc
	v_cndmask_b32_e32 v74, v74, v70, vcc
	v_mad_i64_i32 v[72:73], s[50:51], v70, s40, v[72:73]
	v_cndmask_b32_e32 v77, v65, v76, vcc
	v_cndmask_b32_e32 v76, v78, v79, vcc
	v_lshlrev_b64 v[78:79], 6, v[70:71]
	v_lshlrev_b64 v[70:71], 11, v[70:71]
	v_lshlrev_b64 v[74:75], 11, v[74:75]
	v_lshl_add_u64 v[72:73], v[72:73], 0, v[30:31]
	v_lshl_add_u64 v[70:71], v[76:77], 0, v[74:75]
	v_add_co_u32_e32 v80, vcc, s41, v72
	v_lshl_add_u64 v[78:79], v[26:27], 0, v[78:79]
	v_lshl_add_u64 v[70:71], v[70:71], 0, v[30:31]
	v_addc_co_u32_e32 v81, vcc, 0, v73, vcc
	global_load_dwordx4 v[142:145], v[70:71], off
	s_nop 0
	global_load_dwordx4 v[166:169], v[80:81], off
	s_nop 0
	global_load_dword v245, v[78:79], off
	v_add_u32_e32 v70, 96, v24
	v_add_u32_e32 v74, 0xffffbf80, v70
	v_ashrrev_i32_e32 v71, 31, v70
	v_cmp_gt_i32_e32 vcc, s35, v70
	v_mov_b32_e32 v65, s12
	v_mov_b32_e32 v76, s33
	v_mov_b32_e32 v78, s11
	v_mov_b32_e32 v79, s13
	v_mov_b64_e32 v[72:73], s[30:31]
	v_cndmask_b32_e32 v75, 0, v71, vcc
	v_cndmask_b32_e32 v74, v74, v70, vcc
	v_mad_i64_i32 v[72:73], s[50:51], v70, s40, v[72:73]
	v_cndmask_b32_e32 v77, v65, v76, vcc
	v_cndmask_b32_e32 v76, v78, v79, vcc
	v_lshlrev_b64 v[78:79], 6, v[70:71]
	v_lshlrev_b64 v[70:71], 11, v[70:71]
	v_lshlrev_b64 v[74:75], 11, v[74:75]
	v_lshl_add_u64 v[72:73], v[72:73], 0, v[30:31]
	v_lshl_add_u64 v[70:71], v[76:77], 0, v[74:75]
	v_add_co_u32_e32 v80, vcc, s41, v72
	v_lshl_add_u64 v[78:79], v[26:27], 0, v[78:79]
	v_lshl_add_u64 v[70:71], v[70:71], 0, v[30:31]
	v_addc_co_u32_e32 v81, vcc, 0, v73, vcc
	global_load_dwordx4 v[170:173], v[70:71], off
	s_nop 0
	global_load_dwordx4 v[174:177], v[80:81], off
	s_nop 0
	global_load_dword v246, v[78:79], off
	v_add_u32_e32 v70, 112, v24
	v_add_u32_e32 v74, 0xffffbf80, v70
	v_ashrrev_i32_e32 v71, 31, v70
	v_cmp_gt_i32_e32 vcc, s35, v70
	v_mov_b32_e32 v65, s12
	v_mov_b32_e32 v76, s33
	v_mov_b32_e32 v78, s11
	v_mov_b32_e32 v79, s13
	v_mov_b64_e32 v[72:73], s[30:31]
	v_cndmask_b32_e32 v75, 0, v71, vcc
	v_cndmask_b32_e32 v74, v74, v70, vcc
	v_mad_i64_i32 v[72:73], s[50:51], v70, s40, v[72:73]
	v_cndmask_b32_e32 v77, v65, v76, vcc
	v_cndmask_b32_e32 v76, v78, v79, vcc
	v_lshlrev_b64 v[78:79], 6, v[70:71]
	v_lshlrev_b64 v[70:71], 11, v[70:71]
	v_lshlrev_b64 v[74:75], 11, v[74:75]
	v_lshl_add_u64 v[72:73], v[72:73], 0, v[30:31]
	v_lshl_add_u64 v[70:71], v[76:77], 0, v[74:75]
	v_add_co_u32_e32 v80, vcc, s41, v72
	v_lshl_add_u64 v[78:79], v[26:27], 0, v[78:79]
	v_lshl_add_u64 v[70:71], v[70:71], 0, v[30:31]
	v_addc_co_u32_e32 v81, vcc, 0, v73, vcc
	global_load_dwordx4 v[178:181], v[70:71], off
	s_nop 0
	global_load_dwordx4 v[182:185], v[80:81], off
	s_nop 0
	global_load_dword v247, v[78:79], off
	v_add_u32_e32 v70, 0, v24
	ds_read_b128 v[66:69], v64
	v_ashrrev_i32_e32 v71, 31, v70
	v_lshlrev_b64 v[70:71], 11, v[70:71]
	v_lshl_add_u64 v[82:83], v[28:29], 0, v[70:71]
	s_waitcnt vmcnt(21)
	v_mov_b32_e32 v70, v100
	v_mov_b32_e32 v71, v101
	v_mov_b32_e32 v72, v102
	v_mov_b32_e32 v73, v103
	v_mov_b32_e32 v74, v104
	v_mov_b32_e32 v75, v105
	v_mov_b32_e32 v76, v106
	v_mov_b32_e32 v77, v107
	v_mov_b32_e32 v78, v240
	s_waitcnt lgkmcnt(0)
	v_cvt_f32_f16_sdwa v81, v66 dst_sel:DWORD dst_unused:UNUSED_PAD src0_sel:WORD_1
	v_cvt_f32_f16_e32 v80, v66
	v_cvt_f32_f16_sdwa v85, v67 dst_sel:DWORD dst_unused:UNUSED_PAD src0_sel:WORD_1
	v_cvt_f32_f16_e32 v84, v67
	v_cvt_f32_f16_sdwa v67, v68 dst_sel:DWORD dst_unused:UNUSED_PAD src0_sel:WORD_1
	v_cvt_f32_f16_e32 v66, v68
	v_cvt_f32_f16_sdwa v87, v69 dst_sel:DWORD dst_unused:UNUSED_PAD src0_sel:WORD_1
	v_cvt_f32_f16_e32 v86, v69
	v_add_u32_e32 v64, 0x1000, v64
	v_cvt_f32_f16_e32 v90, v70
	v_cvt_f32_f16_sdwa v91, v70 dst_sel:DWORD dst_unused:UNUSED_PAD src0_sel:WORD_1
	v_cvt_f32_f16_e32 v92, v71
	v_cvt_f32_f16_sdwa v93, v71 dst_sel:DWORD dst_unused:UNUSED_PAD src0_sel:WORD_1
	v_cvt_f32_f16_e32 v94, v72
	v_cvt_f32_f16_e32 v96, v73
	v_cvt_f32_f16_sdwa v97, v73 dst_sel:DWORD dst_unused:UNUSED_PAD src0_sel:WORD_1
	v_cvt_f32_f16_sdwa v95, v72 dst_sel:DWORD dst_unused:UNUSED_PAD src0_sel:WORD_1
	v_cvt_f32_f16_e32 v68, v74
	v_cvt_f32_f16_sdwa v69, v74 dst_sel:DWORD dst_unused:UNUSED_PAD src0_sel:WORD_1
	v_pk_add_f32 v[92:93], v[92:93], v[96:97]
	v_pk_add_f32 v[90:91], v[90:91], v[94:95]
	v_cvt_f32_f16_e32 v74, v75
	v_pk_mov_b32 v[94:95], v[90:91], v[92:93] op_sel:[1,0]
	v_mov_b32_e32 v91, v93
	v_pk_add_f32 v[90:91], v[94:95], v[90:91]
	v_cvt_f32_f16_sdwa v75, v75 dst_sel:DWORD dst_unused:UNUSED_PAD src0_sel:WORD_1
	v_add_f32_e32 v65, v90, v91
	v_cvt_f32_f16_e32 v88, v76
	v_cvt_f32_f16_sdwa v89, v76 dst_sel:DWORD dst_unused:UNUSED_PAD src0_sel:WORD_1
	v_add_f32_dpp v65, v65, v65 quad_perm:[1,0,3,2] row_mask:0xf bank_mask:0xf bound_ctrl:1
	v_cvt_f32_f16_e32 v76, v77
	v_cvt_f32_f16_sdwa v77, v77 dst_sel:DWORD dst_unused:UNUSED_PAD src0_sel:WORD_1
	v_add_f32_dpp v65, v65, v65 quad_perm:[2,3,0,1] row_mask:0xf bank_mask:0xf bound_ctrl:1
	s_nop 1
	v_add_f32_dpp v65, v65, v65 row_half_mirror row_mask:0xf bank_mask:0xf bound_ctrl:1
	v_fma_mix_f32 v91, v65, s42, v70 op_sel:[0,0,1] op_sel_hi:[0,0,1]
	v_fma_mix_f32 v90, v65, s42, v70 op_sel_hi:[0,0,1]
	v_fma_mix_f32 v93, v65, s42, v71 op_sel:[0,0,1] op_sel_hi:[0,0,1]
	v_fma_mix_f32 v92, v65, s42, v71 op_sel_hi:[0,0,1]
	v_fma_mix_f32 v71, v65, s42, v73 op_sel:[0,0,1] op_sel_hi:[0,0,1]
	v_fma_mix_f32 v70, v65, s42, v73 op_sel_hi:[0,0,1]
	v_fma_mix_f32 v73, v65, s42, v72 op_sel:[0,0,1] op_sel_hi:[0,0,1]
	v_fma_mix_f32 v72, v65, s42, v72 op_sel_hi:[0,0,1]
	v_pk_mul_f32 v[94:95], v[72:73], v[72:73]
	v_pk_mul_f32 v[96:97], v[70:71], v[70:71]
	v_pk_fma_f32 v[94:95], v[90:91], v[90:91], v[94:95]
	v_pk_fma_f32 v[96:97], v[92:93], v[92:93], v[96:97]
	s_nop 0
	v_pk_mov_b32 v[98:99], v[94:95], v[96:97] op_sel:[1,0]
	v_mov_b32_e32 v95, v97
	v_pk_add_f32 v[94:95], v[98:99], v[94:95]
	s_nop 0
	v_add_f32_e32 v65, v94, v95
	s_nop 1
	v_add_f32_dpp v65, v65, v65 quad_perm:[1,0,3,2] row_mask:0xf bank_mask:0xf bound_ctrl:1
	s_nop 1
	v_add_f32_dpp v65, v65, v65 quad_perm:[2,3,0,1] row_mask:0xf bank_mask:0xf bound_ctrl:1
	s_nop 1
	v_add_f32_dpp v65, v65, v65 row_half_mirror row_mask:0xf bank_mask:0xf bound_ctrl:1
	v_fmamk_f32 v65, v65, 0x3c800000, v63
	v_mul_f32_e32 v79, 0x4b800000, v65
	v_cmp_gt_f32_e32 vcc, s43, v65
	s_nop 1
	v_cndmask_b32_e32 v65, v65, v79, vcc
	v_rsq_f32_e32 v65, v65
	s_nop 0
	v_mul_f32_e32 v79, 0x45800000, v65
	v_cndmask_b32_e32 v94, v65, v79, vcc
	v_pk_mul_f32 v[90:91], v[90:91], v[94:95] op_sel_hi:[1,0]
	v_pk_mul_f32 v[92:93], v[92:93], v[94:95] op_sel_hi:[1,0]
	v_pk_mul_f32 v[72:73], v[72:73], v[94:95] op_sel_hi:[1,0]
	v_pk_mul_f32 v[70:71], v[70:71], v[94:95] op_sel_hi:[1,0]
	v_pk_fma_f32 v[92:93], v[6:7], v[92:93], v[14:15]
	v_pk_fma_f32 v[90:91], v[4:5], v[90:91], v[12:13]
	v_pk_fma_f32 v[70:71], v[2:3], v[70:71], v[10:11]
	v_pk_fma_f32 v[72:73], v[0:1], v[72:73], v[8:9]
	v_pk_fma_f32 v[68:69], v[78:79], v[68:69], v[90:91] op_sel_hi:[0,1,1]
	v_pk_fma_f32 v[74:75], v[78:79], v[74:75], v[92:93] op_sel_hi:[0,1,1]
	v_pk_fma_f32 v[72:73], v[78:79], v[88:89], v[72:73] op_sel_hi:[0,1,1]
	v_pk_fma_f32 v[70:71], v[78:79], v[76:77], v[70:71] op_sel_hi:[0,1,1]
	v_pk_mul_f32 v[74:75], v[84:85], v[74:75]
	v_pk_mul_f32 v[76:77], v[80:81], v[68:69]
	v_pk_mul_f32 v[68:69], v[86:87], v[70:71]
	v_pk_mul_f32 v[66:67], v[66:67], v[72:73]
	v_cvt_pk_f16_f32 v69, v68, v69
	v_cvt_pk_f16_f32 v68, v66, v67
	v_cvt_pk_f16_f32 v67, v74, v75
	v_cvt_pk_f16_f32 v66, v76, v77
	global_store_dwordx4 v[82:83], v[66:69], off
	v_add_u32_e32 v70, 16, v24
	ds_read_b128 v[66:69], v64
	v_ashrrev_i32_e32 v71, 31, v70
	v_lshlrev_b64 v[70:71], 11, v[70:71]
	v_lshl_add_u64 v[82:83], v[28:29], 0, v[70:71]
	s_waitcnt vmcnt(18)
	v_mov_b32_e32 v70, v108
	v_mov_b32_e32 v71, v109
	v_mov_b32_e32 v72, v110
	v_mov_b32_e32 v73, v111
	v_mov_b32_e32 v74, v112
	v_mov_b32_e32 v75, v113
	v_mov_b32_e32 v76, v114
	v_mov_b32_e32 v77, v115
	v_mov_b32_e32 v78, v241
	s_waitcnt lgkmcnt(0)
	v_cvt_f32_f16_sdwa v81, v66 dst_sel:DWORD dst_unused:UNUSED_PAD src0_sel:WORD_1
	v_cvt_f32_f16_e32 v80, v66
	v_cvt_f32_f16_sdwa v85, v67 dst_sel:DWORD dst_unused:UNUSED_PAD src0_sel:WORD_1
	v_cvt_f32_f16_e32 v84, v67
	v_cvt_f32_f16_sdwa v67, v68 dst_sel:DWORD dst_unused:UNUSED_PAD src0_sel:WORD_1
	v_cvt_f32_f16_e32 v66, v68
	v_cvt_f32_f16_sdwa v87, v69 dst_sel:DWORD dst_unused:UNUSED_PAD src0_sel:WORD_1
	v_cvt_f32_f16_e32 v86, v69
	v_add_u32_e32 v64, 0x1000, v64
	v_cvt_f32_f16_e32 v90, v70
	v_cvt_f32_f16_sdwa v91, v70 dst_sel:DWORD dst_unused:UNUSED_PAD src0_sel:WORD_1
	v_cvt_f32_f16_e32 v92, v71
	v_cvt_f32_f16_sdwa v93, v71 dst_sel:DWORD dst_unused:UNUSED_PAD src0_sel:WORD_1
	v_cvt_f32_f16_e32 v94, v72
	v_cvt_f32_f16_e32 v96, v73
	v_cvt_f32_f16_sdwa v97, v73 dst_sel:DWORD dst_unused:UNUSED_PAD src0_sel:WORD_1
	v_cvt_f32_f16_sdwa v95, v72 dst_sel:DWORD dst_unused:UNUSED_PAD src0_sel:WORD_1
	v_cvt_f32_f16_e32 v68, v74
	v_cvt_f32_f16_sdwa v69, v74 dst_sel:DWORD dst_unused:UNUSED_PAD src0_sel:WORD_1
	v_pk_add_f32 v[92:93], v[92:93], v[96:97]
	v_pk_add_f32 v[90:91], v[90:91], v[94:95]
	v_cvt_f32_f16_e32 v74, v75
	v_pk_mov_b32 v[94:95], v[90:91], v[92:93] op_sel:[1,0]
	v_mov_b32_e32 v91, v93
	v_pk_add_f32 v[90:91], v[94:95], v[90:91]
	v_cvt_f32_f16_sdwa v75, v75 dst_sel:DWORD dst_unused:UNUSED_PAD src0_sel:WORD_1
	v_add_f32_e32 v65, v90, v91
	v_cvt_f32_f16_e32 v88, v76
	v_cvt_f32_f16_sdwa v89, v76 dst_sel:DWORD dst_unused:UNUSED_PAD src0_sel:WORD_1
	v_add_f32_dpp v65, v65, v65 quad_perm:[1,0,3,2] row_mask:0xf bank_mask:0xf bound_ctrl:1
	v_cvt_f32_f16_e32 v76, v77
	v_cvt_f32_f16_sdwa v77, v77 dst_sel:DWORD dst_unused:UNUSED_PAD src0_sel:WORD_1
	v_add_f32_dpp v65, v65, v65 quad_perm:[2,3,0,1] row_mask:0xf bank_mask:0xf bound_ctrl:1
	s_nop 1
	v_add_f32_dpp v65, v65, v65 row_half_mirror row_mask:0xf bank_mask:0xf bound_ctrl:1
	v_fma_mix_f32 v91, v65, s42, v70 op_sel:[0,0,1] op_sel_hi:[0,0,1]
	v_fma_mix_f32 v90, v65, s42, v70 op_sel_hi:[0,0,1]
	v_fma_mix_f32 v93, v65, s42, v71 op_sel:[0,0,1] op_sel_hi:[0,0,1]
	v_fma_mix_f32 v92, v65, s42, v71 op_sel_hi:[0,0,1]
	v_fma_mix_f32 v71, v65, s42, v73 op_sel:[0,0,1] op_sel_hi:[0,0,1]
	v_fma_mix_f32 v70, v65, s42, v73 op_sel_hi:[0,0,1]
	v_fma_mix_f32 v73, v65, s42, v72 op_sel:[0,0,1] op_sel_hi:[0,0,1]
	v_fma_mix_f32 v72, v65, s42, v72 op_sel_hi:[0,0,1]
	v_pk_mul_f32 v[94:95], v[72:73], v[72:73]
	v_pk_mul_f32 v[96:97], v[70:71], v[70:71]
	v_pk_fma_f32 v[94:95], v[90:91], v[90:91], v[94:95]
	v_pk_fma_f32 v[96:97], v[92:93], v[92:93], v[96:97]
	s_nop 0
	v_pk_mov_b32 v[98:99], v[94:95], v[96:97] op_sel:[1,0]
	v_mov_b32_e32 v95, v97
	v_pk_add_f32 v[94:95], v[98:99], v[94:95]
	s_nop 0
	v_add_f32_e32 v65, v94, v95
	s_nop 1
	v_add_f32_dpp v65, v65, v65 quad_perm:[1,0,3,2] row_mask:0xf bank_mask:0xf bound_ctrl:1
	s_nop 1
	v_add_f32_dpp v65, v65, v65 quad_perm:[2,3,0,1] row_mask:0xf bank_mask:0xf bound_ctrl:1
	s_nop 1
	v_add_f32_dpp v65, v65, v65 row_half_mirror row_mask:0xf bank_mask:0xf bound_ctrl:1
	v_fmamk_f32 v65, v65, 0x3c800000, v63
	v_mul_f32_e32 v79, 0x4b800000, v65
	v_cmp_gt_f32_e32 vcc, s43, v65
	s_nop 1
	v_cndmask_b32_e32 v65, v65, v79, vcc
	v_rsq_f32_e32 v65, v65
	s_nop 0
	v_mul_f32_e32 v79, 0x45800000, v65
	v_cndmask_b32_e32 v94, v65, v79, vcc
	v_pk_mul_f32 v[90:91], v[90:91], v[94:95] op_sel_hi:[1,0]
	v_pk_mul_f32 v[92:93], v[92:93], v[94:95] op_sel_hi:[1,0]
	v_pk_mul_f32 v[72:73], v[72:73], v[94:95] op_sel_hi:[1,0]
	v_pk_mul_f32 v[70:71], v[70:71], v[94:95] op_sel_hi:[1,0]
	v_pk_fma_f32 v[92:93], v[6:7], v[92:93], v[14:15]
	v_pk_fma_f32 v[90:91], v[4:5], v[90:91], v[12:13]
	v_pk_fma_f32 v[70:71], v[2:3], v[70:71], v[10:11]
	v_pk_fma_f32 v[72:73], v[0:1], v[72:73], v[8:9]
	v_pk_fma_f32 v[68:69], v[78:79], v[68:69], v[90:91] op_sel_hi:[0,1,1]
	v_pk_fma_f32 v[74:75], v[78:79], v[74:75], v[92:93] op_sel_hi:[0,1,1]
	v_pk_fma_f32 v[72:73], v[78:79], v[88:89], v[72:73] op_sel_hi:[0,1,1]
	v_pk_fma_f32 v[70:71], v[78:79], v[76:77], v[70:71] op_sel_hi:[0,1,1]
	v_pk_mul_f32 v[74:75], v[84:85], v[74:75]
	v_pk_mul_f32 v[76:77], v[80:81], v[68:69]
	v_pk_mul_f32 v[68:69], v[86:87], v[70:71]
	v_pk_mul_f32 v[66:67], v[66:67], v[72:73]
	v_cvt_pk_f16_f32 v69, v68, v69
	v_cvt_pk_f16_f32 v68, v66, v67
	v_cvt_pk_f16_f32 v67, v74, v75
	v_cvt_pk_f16_f32 v66, v76, v77
	global_store_dwordx4 v[82:83], v[66:69], off
	v_add_u32_e32 v70, 32, v24
	ds_read_b128 v[66:69], v64
	v_ashrrev_i32_e32 v71, 31, v70
	v_lshlrev_b64 v[70:71], 11, v[70:71]
	v_lshl_add_u64 v[82:83], v[28:29], 0, v[70:71]
	s_waitcnt vmcnt(15)
	v_mov_b32_e32 v70, v116
	v_mov_b32_e32 v71, v117
	v_mov_b32_e32 v72, v118
	v_mov_b32_e32 v73, v119
	v_mov_b32_e32 v74, v120
	v_mov_b32_e32 v75, v121
	v_mov_b32_e32 v76, v122
	v_mov_b32_e32 v77, v123
	v_mov_b32_e32 v78, v242
	s_waitcnt lgkmcnt(0)
	v_cvt_f32_f16_sdwa v81, v66 dst_sel:DWORD dst_unused:UNUSED_PAD src0_sel:WORD_1
	v_cvt_f32_f16_e32 v80, v66
	v_cvt_f32_f16_sdwa v85, v67 dst_sel:DWORD dst_unused:UNUSED_PAD src0_sel:WORD_1
	v_cvt_f32_f16_e32 v84, v67
	v_cvt_f32_f16_sdwa v67, v68 dst_sel:DWORD dst_unused:UNUSED_PAD src0_sel:WORD_1
	v_cvt_f32_f16_e32 v66, v68
	v_cvt_f32_f16_sdwa v87, v69 dst_sel:DWORD dst_unused:UNUSED_PAD src0_sel:WORD_1
	v_cvt_f32_f16_e32 v86, v69
	v_add_u32_e32 v64, 0x1000, v64
	v_cvt_f32_f16_e32 v90, v70
	v_cvt_f32_f16_sdwa v91, v70 dst_sel:DWORD dst_unused:UNUSED_PAD src0_sel:WORD_1
	v_cvt_f32_f16_e32 v92, v71
	v_cvt_f32_f16_sdwa v93, v71 dst_sel:DWORD dst_unused:UNUSED_PAD src0_sel:WORD_1
	v_cvt_f32_f16_e32 v94, v72
	v_cvt_f32_f16_e32 v96, v73
	v_cvt_f32_f16_sdwa v97, v73 dst_sel:DWORD dst_unused:UNUSED_PAD src0_sel:WORD_1
	v_cvt_f32_f16_sdwa v95, v72 dst_sel:DWORD dst_unused:UNUSED_PAD src0_sel:WORD_1
	v_cvt_f32_f16_e32 v68, v74
	v_cvt_f32_f16_sdwa v69, v74 dst_sel:DWORD dst_unused:UNUSED_PAD src0_sel:WORD_1
	v_pk_add_f32 v[92:93], v[92:93], v[96:97]
	v_pk_add_f32 v[90:91], v[90:91], v[94:95]
	v_cvt_f32_f16_e32 v74, v75
	v_pk_mov_b32 v[94:95], v[90:91], v[92:93] op_sel:[1,0]
	v_mov_b32_e32 v91, v93
	v_pk_add_f32 v[90:91], v[94:95], v[90:91]
	v_cvt_f32_f16_sdwa v75, v75 dst_sel:DWORD dst_unused:UNUSED_PAD src0_sel:WORD_1
	v_add_f32_e32 v65, v90, v91
	v_cvt_f32_f16_e32 v88, v76
	v_cvt_f32_f16_sdwa v89, v76 dst_sel:DWORD dst_unused:UNUSED_PAD src0_sel:WORD_1
	v_add_f32_dpp v65, v65, v65 quad_perm:[1,0,3,2] row_mask:0xf bank_mask:0xf bound_ctrl:1
	v_cvt_f32_f16_e32 v76, v77
	v_cvt_f32_f16_sdwa v77, v77 dst_sel:DWORD dst_unused:UNUSED_PAD src0_sel:WORD_1
	v_add_f32_dpp v65, v65, v65 quad_perm:[2,3,0,1] row_mask:0xf bank_mask:0xf bound_ctrl:1
	s_nop 1
	v_add_f32_dpp v65, v65, v65 row_half_mirror row_mask:0xf bank_mask:0xf bound_ctrl:1
	v_fma_mix_f32 v91, v65, s42, v70 op_sel:[0,0,1] op_sel_hi:[0,0,1]
	v_fma_mix_f32 v90, v65, s42, v70 op_sel_hi:[0,0,1]
	v_fma_mix_f32 v93, v65, s42, v71 op_sel:[0,0,1] op_sel_hi:[0,0,1]
	v_fma_mix_f32 v92, v65, s42, v71 op_sel_hi:[0,0,1]
	v_fma_mix_f32 v71, v65, s42, v73 op_sel:[0,0,1] op_sel_hi:[0,0,1]
	v_fma_mix_f32 v70, v65, s42, v73 op_sel_hi:[0,0,1]
	v_fma_mix_f32 v73, v65, s42, v72 op_sel:[0,0,1] op_sel_hi:[0,0,1]
	v_fma_mix_f32 v72, v65, s42, v72 op_sel_hi:[0,0,1]
	v_pk_mul_f32 v[94:95], v[72:73], v[72:73]
	v_pk_mul_f32 v[96:97], v[70:71], v[70:71]
	v_pk_fma_f32 v[94:95], v[90:91], v[90:91], v[94:95]
	v_pk_fma_f32 v[96:97], v[92:93], v[92:93], v[96:97]
	s_nop 0
	v_pk_mov_b32 v[98:99], v[94:95], v[96:97] op_sel:[1,0]
	v_mov_b32_e32 v95, v97
	v_pk_add_f32 v[94:95], v[98:99], v[94:95]
	s_nop 0
	v_add_f32_e32 v65, v94, v95
	s_nop 1
	v_add_f32_dpp v65, v65, v65 quad_perm:[1,0,3,2] row_mask:0xf bank_mask:0xf bound_ctrl:1
	s_nop 1
	v_add_f32_dpp v65, v65, v65 quad_perm:[2,3,0,1] row_mask:0xf bank_mask:0xf bound_ctrl:1
	s_nop 1
	v_add_f32_dpp v65, v65, v65 row_half_mirror row_mask:0xf bank_mask:0xf bound_ctrl:1
	v_fmamk_f32 v65, v65, 0x3c800000, v63
	v_mul_f32_e32 v79, 0x4b800000, v65
	v_cmp_gt_f32_e32 vcc, s43, v65
	s_nop 1
	v_cndmask_b32_e32 v65, v65, v79, vcc
	v_rsq_f32_e32 v65, v65
	s_nop 0
	v_mul_f32_e32 v79, 0x45800000, v65
	v_cndmask_b32_e32 v94, v65, v79, vcc
	v_pk_mul_f32 v[90:91], v[90:91], v[94:95] op_sel_hi:[1,0]
	v_pk_mul_f32 v[92:93], v[92:93], v[94:95] op_sel_hi:[1,0]
	v_pk_mul_f32 v[72:73], v[72:73], v[94:95] op_sel_hi:[1,0]
	v_pk_mul_f32 v[70:71], v[70:71], v[94:95] op_sel_hi:[1,0]
	v_pk_fma_f32 v[92:93], v[6:7], v[92:93], v[14:15]
	v_pk_fma_f32 v[90:91], v[4:5], v[90:91], v[12:13]
	v_pk_fma_f32 v[70:71], v[2:3], v[70:71], v[10:11]
	v_pk_fma_f32 v[72:73], v[0:1], v[72:73], v[8:9]
	v_pk_fma_f32 v[68:69], v[78:79], v[68:69], v[90:91] op_sel_hi:[0,1,1]
	v_pk_fma_f32 v[74:75], v[78:79], v[74:75], v[92:93] op_sel_hi:[0,1,1]
	v_pk_fma_f32 v[72:73], v[78:79], v[88:89], v[72:73] op_sel_hi:[0,1,1]
	v_pk_fma_f32 v[70:71], v[78:79], v[76:77], v[70:71] op_sel_hi:[0,1,1]
	v_pk_mul_f32 v[74:75], v[84:85], v[74:75]
	v_pk_mul_f32 v[76:77], v[80:81], v[68:69]
	v_pk_mul_f32 v[68:69], v[86:87], v[70:71]
	v_pk_mul_f32 v[66:67], v[66:67], v[72:73]
	v_cvt_pk_f16_f32 v69, v68, v69
	v_cvt_pk_f16_f32 v68, v66, v67
	v_cvt_pk_f16_f32 v67, v74, v75
	v_cvt_pk_f16_f32 v66, v76, v77
	global_store_dwordx4 v[82:83], v[66:69], off
	v_add_u32_e32 v70, 48, v24
	ds_read_b128 v[66:69], v64
	v_ashrrev_i32_e32 v71, 31, v70
	v_lshlrev_b64 v[70:71], 11, v[70:71]
	v_lshl_add_u64 v[82:83], v[28:29], 0, v[70:71]
	s_waitcnt vmcnt(12)
	v_mov_b32_e32 v70, v124
	v_mov_b32_e32 v71, v125
	v_mov_b32_e32 v72, v126
	v_mov_b32_e32 v73, v127
	v_mov_b32_e32 v74, v130
	v_mov_b32_e32 v75, v131
	v_mov_b32_e32 v76, v132
	v_mov_b32_e32 v77, v133
	v_mov_b32_e32 v78, v243
	s_waitcnt lgkmcnt(0)
	v_cvt_f32_f16_sdwa v81, v66 dst_sel:DWORD dst_unused:UNUSED_PAD src0_sel:WORD_1
	v_cvt_f32_f16_e32 v80, v66
	v_cvt_f32_f16_sdwa v85, v67 dst_sel:DWORD dst_unused:UNUSED_PAD src0_sel:WORD_1
	v_cvt_f32_f16_e32 v84, v67
	v_cvt_f32_f16_sdwa v67, v68 dst_sel:DWORD dst_unused:UNUSED_PAD src0_sel:WORD_1
	v_cvt_f32_f16_e32 v66, v68
	v_cvt_f32_f16_sdwa v87, v69 dst_sel:DWORD dst_unused:UNUSED_PAD src0_sel:WORD_1
	v_cvt_f32_f16_e32 v86, v69
	v_add_u32_e32 v64, 0x1000, v64
	v_cvt_f32_f16_e32 v90, v70
	v_cvt_f32_f16_sdwa v91, v70 dst_sel:DWORD dst_unused:UNUSED_PAD src0_sel:WORD_1
	v_cvt_f32_f16_e32 v92, v71
	v_cvt_f32_f16_sdwa v93, v71 dst_sel:DWORD dst_unused:UNUSED_PAD src0_sel:WORD_1
	v_cvt_f32_f16_e32 v94, v72
	v_cvt_f32_f16_e32 v96, v73
	v_cvt_f32_f16_sdwa v97, v73 dst_sel:DWORD dst_unused:UNUSED_PAD src0_sel:WORD_1
	v_cvt_f32_f16_sdwa v95, v72 dst_sel:DWORD dst_unused:UNUSED_PAD src0_sel:WORD_1
	v_cvt_f32_f16_e32 v68, v74
	v_cvt_f32_f16_sdwa v69, v74 dst_sel:DWORD dst_unused:UNUSED_PAD src0_sel:WORD_1
	v_pk_add_f32 v[92:93], v[92:93], v[96:97]
	v_pk_add_f32 v[90:91], v[90:91], v[94:95]
	v_cvt_f32_f16_e32 v74, v75
	v_pk_mov_b32 v[94:95], v[90:91], v[92:93] op_sel:[1,0]
	v_mov_b32_e32 v91, v93
	v_pk_add_f32 v[90:91], v[94:95], v[90:91]
	v_cvt_f32_f16_sdwa v75, v75 dst_sel:DWORD dst_unused:UNUSED_PAD src0_sel:WORD_1
	v_add_f32_e32 v65, v90, v91
	v_cvt_f32_f16_e32 v88, v76
	v_cvt_f32_f16_sdwa v89, v76 dst_sel:DWORD dst_unused:UNUSED_PAD src0_sel:WORD_1
	v_add_f32_dpp v65, v65, v65 quad_perm:[1,0,3,2] row_mask:0xf bank_mask:0xf bound_ctrl:1
	v_cvt_f32_f16_e32 v76, v77
	v_cvt_f32_f16_sdwa v77, v77 dst_sel:DWORD dst_unused:UNUSED_PAD src0_sel:WORD_1
	v_add_f32_dpp v65, v65, v65 quad_perm:[2,3,0,1] row_mask:0xf bank_mask:0xf bound_ctrl:1
	s_nop 1
	v_add_f32_dpp v65, v65, v65 row_half_mirror row_mask:0xf bank_mask:0xf bound_ctrl:1
	v_fma_mix_f32 v91, v65, s42, v70 op_sel:[0,0,1] op_sel_hi:[0,0,1]
	v_fma_mix_f32 v90, v65, s42, v70 op_sel_hi:[0,0,1]
	v_fma_mix_f32 v93, v65, s42, v71 op_sel:[0,0,1] op_sel_hi:[0,0,1]
	v_fma_mix_f32 v92, v65, s42, v71 op_sel_hi:[0,0,1]
	v_fma_mix_f32 v71, v65, s42, v73 op_sel:[0,0,1] op_sel_hi:[0,0,1]
	v_fma_mix_f32 v70, v65, s42, v73 op_sel_hi:[0,0,1]
	v_fma_mix_f32 v73, v65, s42, v72 op_sel:[0,0,1] op_sel_hi:[0,0,1]
	v_fma_mix_f32 v72, v65, s42, v72 op_sel_hi:[0,0,1]
	v_pk_mul_f32 v[94:95], v[72:73], v[72:73]
	v_pk_mul_f32 v[96:97], v[70:71], v[70:71]
	v_pk_fma_f32 v[94:95], v[90:91], v[90:91], v[94:95]
	v_pk_fma_f32 v[96:97], v[92:93], v[92:93], v[96:97]
	s_nop 0
	v_pk_mov_b32 v[98:99], v[94:95], v[96:97] op_sel:[1,0]
	v_mov_b32_e32 v95, v97
	v_pk_add_f32 v[94:95], v[98:99], v[94:95]
	s_nop 0
	v_add_f32_e32 v65, v94, v95
	s_nop 1
	v_add_f32_dpp v65, v65, v65 quad_perm:[1,0,3,2] row_mask:0xf bank_mask:0xf bound_ctrl:1
	s_nop 1
	v_add_f32_dpp v65, v65, v65 quad_perm:[2,3,0,1] row_mask:0xf bank_mask:0xf bound_ctrl:1
	s_nop 1
	v_add_f32_dpp v65, v65, v65 row_half_mirror row_mask:0xf bank_mask:0xf bound_ctrl:1
	v_fmamk_f32 v65, v65, 0x3c800000, v63
	v_mul_f32_e32 v79, 0x4b800000, v65
	v_cmp_gt_f32_e32 vcc, s43, v65
	s_nop 1
	v_cndmask_b32_e32 v65, v65, v79, vcc
	v_rsq_f32_e32 v65, v65
	s_nop 0
	v_mul_f32_e32 v79, 0x45800000, v65
	v_cndmask_b32_e32 v94, v65, v79, vcc
	v_pk_mul_f32 v[90:91], v[90:91], v[94:95] op_sel_hi:[1,0]
	v_pk_mul_f32 v[92:93], v[92:93], v[94:95] op_sel_hi:[1,0]
	v_pk_mul_f32 v[72:73], v[72:73], v[94:95] op_sel_hi:[1,0]
	v_pk_mul_f32 v[70:71], v[70:71], v[94:95] op_sel_hi:[1,0]
	v_pk_fma_f32 v[92:93], v[6:7], v[92:93], v[14:15]
	v_pk_fma_f32 v[90:91], v[4:5], v[90:91], v[12:13]
	v_pk_fma_f32 v[70:71], v[2:3], v[70:71], v[10:11]
	v_pk_fma_f32 v[72:73], v[0:1], v[72:73], v[8:9]
	v_pk_fma_f32 v[68:69], v[78:79], v[68:69], v[90:91] op_sel_hi:[0,1,1]
	v_pk_fma_f32 v[74:75], v[78:79], v[74:75], v[92:93] op_sel_hi:[0,1,1]
	v_pk_fma_f32 v[72:73], v[78:79], v[88:89], v[72:73] op_sel_hi:[0,1,1]
	v_pk_fma_f32 v[70:71], v[78:79], v[76:77], v[70:71] op_sel_hi:[0,1,1]
	v_pk_mul_f32 v[74:75], v[84:85], v[74:75]
	v_pk_mul_f32 v[76:77], v[80:81], v[68:69]
	v_pk_mul_f32 v[68:69], v[86:87], v[70:71]
	v_pk_mul_f32 v[66:67], v[66:67], v[72:73]
	v_cvt_pk_f16_f32 v69, v68, v69
	v_cvt_pk_f16_f32 v68, v66, v67
	v_cvt_pk_f16_f32 v67, v74, v75
	v_cvt_pk_f16_f32 v66, v76, v77
	global_store_dwordx4 v[82:83], v[66:69], off
	v_add_u32_e32 v70, 64, v24
	ds_read_b128 v[66:69], v64
	v_ashrrev_i32_e32 v71, 31, v70
	v_lshlrev_b64 v[70:71], 11, v[70:71]
	v_lshl_add_u64 v[82:83], v[28:29], 0, v[70:71]
	s_waitcnt vmcnt(9)
	v_mov_b32_e32 v70, v134
	v_mov_b32_e32 v71, v135
	v_mov_b32_e32 v72, v136
	v_mov_b32_e32 v73, v137
	v_mov_b32_e32 v74, v138
	v_mov_b32_e32 v75, v139
	v_mov_b32_e32 v76, v140
	v_mov_b32_e32 v77, v141
	v_mov_b32_e32 v78, v244
	s_waitcnt lgkmcnt(0)
	v_cvt_f32_f16_sdwa v81, v66 dst_sel:DWORD dst_unused:UNUSED_PAD src0_sel:WORD_1
	v_cvt_f32_f16_e32 v80, v66
	v_cvt_f32_f16_sdwa v85, v67 dst_sel:DWORD dst_unused:UNUSED_PAD src0_sel:WORD_1
	v_cvt_f32_f16_e32 v84, v67
	v_cvt_f32_f16_sdwa v67, v68 dst_sel:DWORD dst_unused:UNUSED_PAD src0_sel:WORD_1
	v_cvt_f32_f16_e32 v66, v68
	v_cvt_f32_f16_sdwa v87, v69 dst_sel:DWORD dst_unused:UNUSED_PAD src0_sel:WORD_1
	v_cvt_f32_f16_e32 v86, v69
	v_add_u32_e32 v64, 0x1000, v64
	v_cvt_f32_f16_e32 v90, v70
	v_cvt_f32_f16_sdwa v91, v70 dst_sel:DWORD dst_unused:UNUSED_PAD src0_sel:WORD_1
	v_cvt_f32_f16_e32 v92, v71
	v_cvt_f32_f16_sdwa v93, v71 dst_sel:DWORD dst_unused:UNUSED_PAD src0_sel:WORD_1
	v_cvt_f32_f16_e32 v94, v72
	v_cvt_f32_f16_e32 v96, v73
	v_cvt_f32_f16_sdwa v97, v73 dst_sel:DWORD dst_unused:UNUSED_PAD src0_sel:WORD_1
	v_cvt_f32_f16_sdwa v95, v72 dst_sel:DWORD dst_unused:UNUSED_PAD src0_sel:WORD_1
	v_cvt_f32_f16_e32 v68, v74
	v_cvt_f32_f16_sdwa v69, v74 dst_sel:DWORD dst_unused:UNUSED_PAD src0_sel:WORD_1
	v_pk_add_f32 v[92:93], v[92:93], v[96:97]
	v_pk_add_f32 v[90:91], v[90:91], v[94:95]
	v_cvt_f32_f16_e32 v74, v75
	v_pk_mov_b32 v[94:95], v[90:91], v[92:93] op_sel:[1,0]
	v_mov_b32_e32 v91, v93
	v_pk_add_f32 v[90:91], v[94:95], v[90:91]
	v_cvt_f32_f16_sdwa v75, v75 dst_sel:DWORD dst_unused:UNUSED_PAD src0_sel:WORD_1
	v_add_f32_e32 v65, v90, v91
	v_cvt_f32_f16_e32 v88, v76
	v_cvt_f32_f16_sdwa v89, v76 dst_sel:DWORD dst_unused:UNUSED_PAD src0_sel:WORD_1
	v_add_f32_dpp v65, v65, v65 quad_perm:[1,0,3,2] row_mask:0xf bank_mask:0xf bound_ctrl:1
	v_cvt_f32_f16_e32 v76, v77
	v_cvt_f32_f16_sdwa v77, v77 dst_sel:DWORD dst_unused:UNUSED_PAD src0_sel:WORD_1
	v_add_f32_dpp v65, v65, v65 quad_perm:[2,3,0,1] row_mask:0xf bank_mask:0xf bound_ctrl:1
	s_nop 1
	v_add_f32_dpp v65, v65, v65 row_half_mirror row_mask:0xf bank_mask:0xf bound_ctrl:1
	v_fma_mix_f32 v91, v65, s42, v70 op_sel:[0,0,1] op_sel_hi:[0,0,1]
	v_fma_mix_f32 v90, v65, s42, v70 op_sel_hi:[0,0,1]
	v_fma_mix_f32 v93, v65, s42, v71 op_sel:[0,0,1] op_sel_hi:[0,0,1]
	v_fma_mix_f32 v92, v65, s42, v71 op_sel_hi:[0,0,1]
	v_fma_mix_f32 v71, v65, s42, v73 op_sel:[0,0,1] op_sel_hi:[0,0,1]
	v_fma_mix_f32 v70, v65, s42, v73 op_sel_hi:[0,0,1]
	v_fma_mix_f32 v73, v65, s42, v72 op_sel:[0,0,1] op_sel_hi:[0,0,1]
	v_fma_mix_f32 v72, v65, s42, v72 op_sel_hi:[0,0,1]
	v_pk_mul_f32 v[94:95], v[72:73], v[72:73]
	v_pk_mul_f32 v[96:97], v[70:71], v[70:71]
	v_pk_fma_f32 v[94:95], v[90:91], v[90:91], v[94:95]
	v_pk_fma_f32 v[96:97], v[92:93], v[92:93], v[96:97]
	s_nop 0
	v_pk_mov_b32 v[98:99], v[94:95], v[96:97] op_sel:[1,0]
	v_mov_b32_e32 v95, v97
	v_pk_add_f32 v[94:95], v[98:99], v[94:95]
	s_nop 0
	v_add_f32_e32 v65, v94, v95
	s_nop 1
	v_add_f32_dpp v65, v65, v65 quad_perm:[1,0,3,2] row_mask:0xf bank_mask:0xf bound_ctrl:1
	s_nop 1
	v_add_f32_dpp v65, v65, v65 quad_perm:[2,3,0,1] row_mask:0xf bank_mask:0xf bound_ctrl:1
	s_nop 1
	v_add_f32_dpp v65, v65, v65 row_half_mirror row_mask:0xf bank_mask:0xf bound_ctrl:1
	v_fmamk_f32 v65, v65, 0x3c800000, v63
	v_mul_f32_e32 v79, 0x4b800000, v65
	v_cmp_gt_f32_e32 vcc, s43, v65
	s_nop 1
	v_cndmask_b32_e32 v65, v65, v79, vcc
	v_rsq_f32_e32 v65, v65
	s_nop 0
	v_mul_f32_e32 v79, 0x45800000, v65
	v_cndmask_b32_e32 v94, v65, v79, vcc
	v_pk_mul_f32 v[90:91], v[90:91], v[94:95] op_sel_hi:[1,0]
	v_pk_mul_f32 v[92:93], v[92:93], v[94:95] op_sel_hi:[1,0]
	v_pk_mul_f32 v[72:73], v[72:73], v[94:95] op_sel_hi:[1,0]
	v_pk_mul_f32 v[70:71], v[70:71], v[94:95] op_sel_hi:[1,0]
	v_pk_fma_f32 v[92:93], v[6:7], v[92:93], v[14:15]
	v_pk_fma_f32 v[90:91], v[4:5], v[90:91], v[12:13]
	v_pk_fma_f32 v[70:71], v[2:3], v[70:71], v[10:11]
	v_pk_fma_f32 v[72:73], v[0:1], v[72:73], v[8:9]
	v_pk_fma_f32 v[68:69], v[78:79], v[68:69], v[90:91] op_sel_hi:[0,1,1]
	v_pk_fma_f32 v[74:75], v[78:79], v[74:75], v[92:93] op_sel_hi:[0,1,1]
	v_pk_fma_f32 v[72:73], v[78:79], v[88:89], v[72:73] op_sel_hi:[0,1,1]
	v_pk_fma_f32 v[70:71], v[78:79], v[76:77], v[70:71] op_sel_hi:[0,1,1]
	v_pk_mul_f32 v[74:75], v[84:85], v[74:75]
	v_pk_mul_f32 v[76:77], v[80:81], v[68:69]
	v_pk_mul_f32 v[68:69], v[86:87], v[70:71]
	v_pk_mul_f32 v[66:67], v[66:67], v[72:73]
	v_cvt_pk_f16_f32 v69, v68, v69
	v_cvt_pk_f16_f32 v68, v66, v67
	v_cvt_pk_f16_f32 v67, v74, v75
	v_cvt_pk_f16_f32 v66, v76, v77
	global_store_dwordx4 v[82:83], v[66:69], off
	v_add_u32_e32 v70, 80, v24
	ds_read_b128 v[66:69], v64
	v_ashrrev_i32_e32 v71, 31, v70
	v_lshlrev_b64 v[70:71], 11, v[70:71]
	v_lshl_add_u64 v[82:83], v[28:29], 0, v[70:71]
	s_waitcnt vmcnt(6)
	v_mov_b32_e32 v70, v142
	v_mov_b32_e32 v71, v143
	v_mov_b32_e32 v72, v144
	v_mov_b32_e32 v73, v145
	v_mov_b32_e32 v74, v166
	v_mov_b32_e32 v75, v167
	v_mov_b32_e32 v76, v168
	v_mov_b32_e32 v77, v169
	v_mov_b32_e32 v78, v245
	s_waitcnt lgkmcnt(0)
	v_cvt_f32_f16_sdwa v81, v66 dst_sel:DWORD dst_unused:UNUSED_PAD src0_sel:WORD_1
	v_cvt_f32_f16_e32 v80, v66
	v_cvt_f32_f16_sdwa v85, v67 dst_sel:DWORD dst_unused:UNUSED_PAD src0_sel:WORD_1
	v_cvt_f32_f16_e32 v84, v67
	v_cvt_f32_f16_sdwa v67, v68 dst_sel:DWORD dst_unused:UNUSED_PAD src0_sel:WORD_1
	v_cvt_f32_f16_e32 v66, v68
	v_cvt_f32_f16_sdwa v87, v69 dst_sel:DWORD dst_unused:UNUSED_PAD src0_sel:WORD_1
	v_cvt_f32_f16_e32 v86, v69
	v_add_u32_e32 v64, 0x1000, v64
	v_cvt_f32_f16_e32 v90, v70
	v_cvt_f32_f16_sdwa v91, v70 dst_sel:DWORD dst_unused:UNUSED_PAD src0_sel:WORD_1
	v_cvt_f32_f16_e32 v92, v71
	v_cvt_f32_f16_sdwa v93, v71 dst_sel:DWORD dst_unused:UNUSED_PAD src0_sel:WORD_1
	v_cvt_f32_f16_e32 v94, v72
	v_cvt_f32_f16_e32 v96, v73
	v_cvt_f32_f16_sdwa v97, v73 dst_sel:DWORD dst_unused:UNUSED_PAD src0_sel:WORD_1
	v_cvt_f32_f16_sdwa v95, v72 dst_sel:DWORD dst_unused:UNUSED_PAD src0_sel:WORD_1
	v_cvt_f32_f16_e32 v68, v74
	v_cvt_f32_f16_sdwa v69, v74 dst_sel:DWORD dst_unused:UNUSED_PAD src0_sel:WORD_1
	v_pk_add_f32 v[92:93], v[92:93], v[96:97]
	v_pk_add_f32 v[90:91], v[90:91], v[94:95]
	v_cvt_f32_f16_e32 v74, v75
	v_pk_mov_b32 v[94:95], v[90:91], v[92:93] op_sel:[1,0]
	v_mov_b32_e32 v91, v93
	v_pk_add_f32 v[90:91], v[94:95], v[90:91]
	v_cvt_f32_f16_sdwa v75, v75 dst_sel:DWORD dst_unused:UNUSED_PAD src0_sel:WORD_1
	v_add_f32_e32 v65, v90, v91
	v_cvt_f32_f16_e32 v88, v76
	v_cvt_f32_f16_sdwa v89, v76 dst_sel:DWORD dst_unused:UNUSED_PAD src0_sel:WORD_1
	v_add_f32_dpp v65, v65, v65 quad_perm:[1,0,3,2] row_mask:0xf bank_mask:0xf bound_ctrl:1
	v_cvt_f32_f16_e32 v76, v77
	v_cvt_f32_f16_sdwa v77, v77 dst_sel:DWORD dst_unused:UNUSED_PAD src0_sel:WORD_1
	v_add_f32_dpp v65, v65, v65 quad_perm:[2,3,0,1] row_mask:0xf bank_mask:0xf bound_ctrl:1
	s_nop 1
	v_add_f32_dpp v65, v65, v65 row_half_mirror row_mask:0xf bank_mask:0xf bound_ctrl:1
	v_fma_mix_f32 v91, v65, s42, v70 op_sel:[0,0,1] op_sel_hi:[0,0,1]
	v_fma_mix_f32 v90, v65, s42, v70 op_sel_hi:[0,0,1]
	v_fma_mix_f32 v93, v65, s42, v71 op_sel:[0,0,1] op_sel_hi:[0,0,1]
	v_fma_mix_f32 v92, v65, s42, v71 op_sel_hi:[0,0,1]
	v_fma_mix_f32 v71, v65, s42, v73 op_sel:[0,0,1] op_sel_hi:[0,0,1]
	v_fma_mix_f32 v70, v65, s42, v73 op_sel_hi:[0,0,1]
	v_fma_mix_f32 v73, v65, s42, v72 op_sel:[0,0,1] op_sel_hi:[0,0,1]
	v_fma_mix_f32 v72, v65, s42, v72 op_sel_hi:[0,0,1]
	v_pk_mul_f32 v[94:95], v[72:73], v[72:73]
	v_pk_mul_f32 v[96:97], v[70:71], v[70:71]
	v_pk_fma_f32 v[94:95], v[90:91], v[90:91], v[94:95]
	v_pk_fma_f32 v[96:97], v[92:93], v[92:93], v[96:97]
	s_nop 0
	v_pk_mov_b32 v[98:99], v[94:95], v[96:97] op_sel:[1,0]
	v_mov_b32_e32 v95, v97
	v_pk_add_f32 v[94:95], v[98:99], v[94:95]
	s_nop 0
	v_add_f32_e32 v65, v94, v95
	s_nop 1
	v_add_f32_dpp v65, v65, v65 quad_perm:[1,0,3,2] row_mask:0xf bank_mask:0xf bound_ctrl:1
	s_nop 1
	v_add_f32_dpp v65, v65, v65 quad_perm:[2,3,0,1] row_mask:0xf bank_mask:0xf bound_ctrl:1
	s_nop 1
	v_add_f32_dpp v65, v65, v65 row_half_mirror row_mask:0xf bank_mask:0xf bound_ctrl:1
	v_fmamk_f32 v65, v65, 0x3c800000, v63
	v_mul_f32_e32 v79, 0x4b800000, v65
	v_cmp_gt_f32_e32 vcc, s43, v65
	s_nop 1
	v_cndmask_b32_e32 v65, v65, v79, vcc
	v_rsq_f32_e32 v65, v65
	s_nop 0
	v_mul_f32_e32 v79, 0x45800000, v65
	v_cndmask_b32_e32 v94, v65, v79, vcc
	v_pk_mul_f32 v[90:91], v[90:91], v[94:95] op_sel_hi:[1,0]
	v_pk_mul_f32 v[92:93], v[92:93], v[94:95] op_sel_hi:[1,0]
	v_pk_mul_f32 v[72:73], v[72:73], v[94:95] op_sel_hi:[1,0]
	v_pk_mul_f32 v[70:71], v[70:71], v[94:95] op_sel_hi:[1,0]
	v_pk_fma_f32 v[92:93], v[6:7], v[92:93], v[14:15]
	v_pk_fma_f32 v[90:91], v[4:5], v[90:91], v[12:13]
	v_pk_fma_f32 v[70:71], v[2:3], v[70:71], v[10:11]
	v_pk_fma_f32 v[72:73], v[0:1], v[72:73], v[8:9]
	v_pk_fma_f32 v[68:69], v[78:79], v[68:69], v[90:91] op_sel_hi:[0,1,1]
	v_pk_fma_f32 v[74:75], v[78:79], v[74:75], v[92:93] op_sel_hi:[0,1,1]
	v_pk_fma_f32 v[72:73], v[78:79], v[88:89], v[72:73] op_sel_hi:[0,1,1]
	v_pk_fma_f32 v[70:71], v[78:79], v[76:77], v[70:71] op_sel_hi:[0,1,1]
	v_pk_mul_f32 v[74:75], v[84:85], v[74:75]
	v_pk_mul_f32 v[76:77], v[80:81], v[68:69]
	v_pk_mul_f32 v[68:69], v[86:87], v[70:71]
	v_pk_mul_f32 v[66:67], v[66:67], v[72:73]
	v_cvt_pk_f16_f32 v69, v68, v69
	v_cvt_pk_f16_f32 v68, v66, v67
	v_cvt_pk_f16_f32 v67, v74, v75
	v_cvt_pk_f16_f32 v66, v76, v77
	global_store_dwordx4 v[82:83], v[66:69], off
	v_add_u32_e32 v70, 96, v24
	ds_read_b128 v[66:69], v64
	v_ashrrev_i32_e32 v71, 31, v70
	v_lshlrev_b64 v[70:71], 11, v[70:71]
	v_lshl_add_u64 v[82:83], v[28:29], 0, v[70:71]
	s_waitcnt vmcnt(3)
	v_mov_b32_e32 v70, v170
	v_mov_b32_e32 v71, v171
	v_mov_b32_e32 v72, v172
	v_mov_b32_e32 v73, v173
	v_mov_b32_e32 v74, v174
	v_mov_b32_e32 v75, v175
	v_mov_b32_e32 v76, v176
	v_mov_b32_e32 v77, v177
	v_mov_b32_e32 v78, v246
	s_waitcnt lgkmcnt(0)
	v_cvt_f32_f16_sdwa v81, v66 dst_sel:DWORD dst_unused:UNUSED_PAD src0_sel:WORD_1
	v_cvt_f32_f16_e32 v80, v66
	v_cvt_f32_f16_sdwa v85, v67 dst_sel:DWORD dst_unused:UNUSED_PAD src0_sel:WORD_1
	v_cvt_f32_f16_e32 v84, v67
	v_cvt_f32_f16_sdwa v67, v68 dst_sel:DWORD dst_unused:UNUSED_PAD src0_sel:WORD_1
	v_cvt_f32_f16_e32 v66, v68
	v_cvt_f32_f16_sdwa v87, v69 dst_sel:DWORD dst_unused:UNUSED_PAD src0_sel:WORD_1
	v_cvt_f32_f16_e32 v86, v69
	v_add_u32_e32 v64, 0x1000, v64
	v_cvt_f32_f16_e32 v90, v70
	v_cvt_f32_f16_sdwa v91, v70 dst_sel:DWORD dst_unused:UNUSED_PAD src0_sel:WORD_1
	v_cvt_f32_f16_e32 v92, v71
	v_cvt_f32_f16_sdwa v93, v71 dst_sel:DWORD dst_unused:UNUSED_PAD src0_sel:WORD_1
	v_cvt_f32_f16_e32 v94, v72
	v_cvt_f32_f16_e32 v96, v73
	v_cvt_f32_f16_sdwa v97, v73 dst_sel:DWORD dst_unused:UNUSED_PAD src0_sel:WORD_1
	v_cvt_f32_f16_sdwa v95, v72 dst_sel:DWORD dst_unused:UNUSED_PAD src0_sel:WORD_1
	v_cvt_f32_f16_e32 v68, v74
	v_cvt_f32_f16_sdwa v69, v74 dst_sel:DWORD dst_unused:UNUSED_PAD src0_sel:WORD_1
	v_pk_add_f32 v[92:93], v[92:93], v[96:97]
	v_pk_add_f32 v[90:91], v[90:91], v[94:95]
	v_cvt_f32_f16_e32 v74, v75
	v_pk_mov_b32 v[94:95], v[90:91], v[92:93] op_sel:[1,0]
	v_mov_b32_e32 v91, v93
	v_pk_add_f32 v[90:91], v[94:95], v[90:91]
	v_cvt_f32_f16_sdwa v75, v75 dst_sel:DWORD dst_unused:UNUSED_PAD src0_sel:WORD_1
	v_add_f32_e32 v65, v90, v91
	v_cvt_f32_f16_e32 v88, v76
	v_cvt_f32_f16_sdwa v89, v76 dst_sel:DWORD dst_unused:UNUSED_PAD src0_sel:WORD_1
	v_add_f32_dpp v65, v65, v65 quad_perm:[1,0,3,2] row_mask:0xf bank_mask:0xf bound_ctrl:1
	v_cvt_f32_f16_e32 v76, v77
	v_cvt_f32_f16_sdwa v77, v77 dst_sel:DWORD dst_unused:UNUSED_PAD src0_sel:WORD_1
	v_add_f32_dpp v65, v65, v65 quad_perm:[2,3,0,1] row_mask:0xf bank_mask:0xf bound_ctrl:1
	s_nop 1
	v_add_f32_dpp v65, v65, v65 row_half_mirror row_mask:0xf bank_mask:0xf bound_ctrl:1
	v_fma_mix_f32 v91, v65, s42, v70 op_sel:[0,0,1] op_sel_hi:[0,0,1]
	v_fma_mix_f32 v90, v65, s42, v70 op_sel_hi:[0,0,1]
	v_fma_mix_f32 v93, v65, s42, v71 op_sel:[0,0,1] op_sel_hi:[0,0,1]
	v_fma_mix_f32 v92, v65, s42, v71 op_sel_hi:[0,0,1]
	v_fma_mix_f32 v71, v65, s42, v73 op_sel:[0,0,1] op_sel_hi:[0,0,1]
	v_fma_mix_f32 v70, v65, s42, v73 op_sel_hi:[0,0,1]
	v_fma_mix_f32 v73, v65, s42, v72 op_sel:[0,0,1] op_sel_hi:[0,0,1]
	v_fma_mix_f32 v72, v65, s42, v72 op_sel_hi:[0,0,1]
	v_pk_mul_f32 v[94:95], v[72:73], v[72:73]
	v_pk_mul_f32 v[96:97], v[70:71], v[70:71]
	v_pk_fma_f32 v[94:95], v[90:91], v[90:91], v[94:95]
	v_pk_fma_f32 v[96:97], v[92:93], v[92:93], v[96:97]
	s_nop 0
	v_pk_mov_b32 v[98:99], v[94:95], v[96:97] op_sel:[1,0]
	v_mov_b32_e32 v95, v97
	v_pk_add_f32 v[94:95], v[98:99], v[94:95]
	s_nop 0
	v_add_f32_e32 v65, v94, v95
	s_nop 1
	v_add_f32_dpp v65, v65, v65 quad_perm:[1,0,3,2] row_mask:0xf bank_mask:0xf bound_ctrl:1
	s_nop 1
	v_add_f32_dpp v65, v65, v65 quad_perm:[2,3,0,1] row_mask:0xf bank_mask:0xf bound_ctrl:1
	s_nop 1
	v_add_f32_dpp v65, v65, v65 row_half_mirror row_mask:0xf bank_mask:0xf bound_ctrl:1
	v_fmamk_f32 v65, v65, 0x3c800000, v63
	v_mul_f32_e32 v79, 0x4b800000, v65
	v_cmp_gt_f32_e32 vcc, s43, v65
	s_nop 1
	v_cndmask_b32_e32 v65, v65, v79, vcc
	v_rsq_f32_e32 v65, v65
	s_nop 0
	v_mul_f32_e32 v79, 0x45800000, v65
	v_cndmask_b32_e32 v94, v65, v79, vcc
	v_pk_mul_f32 v[90:91], v[90:91], v[94:95] op_sel_hi:[1,0]
	v_pk_mul_f32 v[92:93], v[92:93], v[94:95] op_sel_hi:[1,0]
	v_pk_mul_f32 v[72:73], v[72:73], v[94:95] op_sel_hi:[1,0]
	v_pk_mul_f32 v[70:71], v[70:71], v[94:95] op_sel_hi:[1,0]
	v_pk_fma_f32 v[92:93], v[6:7], v[92:93], v[14:15]
	v_pk_fma_f32 v[90:91], v[4:5], v[90:91], v[12:13]
	v_pk_fma_f32 v[70:71], v[2:3], v[70:71], v[10:11]
	v_pk_fma_f32 v[72:73], v[0:1], v[72:73], v[8:9]
	v_pk_fma_f32 v[68:69], v[78:79], v[68:69], v[90:91] op_sel_hi:[0,1,1]
	v_pk_fma_f32 v[74:75], v[78:79], v[74:75], v[92:93] op_sel_hi:[0,1,1]
	v_pk_fma_f32 v[72:73], v[78:79], v[88:89], v[72:73] op_sel_hi:[0,1,1]
	v_pk_fma_f32 v[70:71], v[78:79], v[76:77], v[70:71] op_sel_hi:[0,1,1]
	v_pk_mul_f32 v[74:75], v[84:85], v[74:75]
	v_pk_mul_f32 v[76:77], v[80:81], v[68:69]
	v_pk_mul_f32 v[68:69], v[86:87], v[70:71]
	v_pk_mul_f32 v[66:67], v[66:67], v[72:73]
	v_cvt_pk_f16_f32 v69, v68, v69
	v_cvt_pk_f16_f32 v68, v66, v67
	v_cvt_pk_f16_f32 v67, v74, v75
	v_cvt_pk_f16_f32 v66, v76, v77
	global_store_dwordx4 v[82:83], v[66:69], off
	v_add_u32_e32 v70, 112, v24
	ds_read_b128 v[66:69], v64
	v_ashrrev_i32_e32 v71, 31, v70
	v_lshlrev_b64 v[70:71], 11, v[70:71]
	v_lshl_add_u64 v[82:83], v[28:29], 0, v[70:71]
	s_waitcnt vmcnt(0)
	v_mov_b32_e32 v70, v178
	v_mov_b32_e32 v71, v179
	v_mov_b32_e32 v72, v180
	v_mov_b32_e32 v73, v181
	v_mov_b32_e32 v74, v182
	v_mov_b32_e32 v75, v183
	v_mov_b32_e32 v76, v184
	v_mov_b32_e32 v77, v185
	v_mov_b32_e32 v78, v247
	s_waitcnt lgkmcnt(0)
	v_cvt_f32_f16_sdwa v81, v66 dst_sel:DWORD dst_unused:UNUSED_PAD src0_sel:WORD_1
	v_cvt_f32_f16_e32 v80, v66
	v_cvt_f32_f16_sdwa v85, v67 dst_sel:DWORD dst_unused:UNUSED_PAD src0_sel:WORD_1
	v_cvt_f32_f16_e32 v84, v67
	v_cvt_f32_f16_sdwa v67, v68 dst_sel:DWORD dst_unused:UNUSED_PAD src0_sel:WORD_1
	v_cvt_f32_f16_e32 v66, v68
	v_cvt_f32_f16_sdwa v87, v69 dst_sel:DWORD dst_unused:UNUSED_PAD src0_sel:WORD_1
	v_cvt_f32_f16_e32 v86, v69
	v_add_u32_e32 v64, 0x1000, v64
	v_cvt_f32_f16_e32 v90, v70
	v_cvt_f32_f16_sdwa v91, v70 dst_sel:DWORD dst_unused:UNUSED_PAD src0_sel:WORD_1
	v_cvt_f32_f16_e32 v92, v71
	v_cvt_f32_f16_sdwa v93, v71 dst_sel:DWORD dst_unused:UNUSED_PAD src0_sel:WORD_1
	v_cvt_f32_f16_e32 v94, v72
	v_cvt_f32_f16_e32 v96, v73
	v_cvt_f32_f16_sdwa v97, v73 dst_sel:DWORD dst_unused:UNUSED_PAD src0_sel:WORD_1
	v_cvt_f32_f16_sdwa v95, v72 dst_sel:DWORD dst_unused:UNUSED_PAD src0_sel:WORD_1
	v_cvt_f32_f16_e32 v68, v74
	v_cvt_f32_f16_sdwa v69, v74 dst_sel:DWORD dst_unused:UNUSED_PAD src0_sel:WORD_1
	v_pk_add_f32 v[92:93], v[92:93], v[96:97]
	v_pk_add_f32 v[90:91], v[90:91], v[94:95]
	v_cvt_f32_f16_e32 v74, v75
	v_pk_mov_b32 v[94:95], v[90:91], v[92:93] op_sel:[1,0]
	v_mov_b32_e32 v91, v93
	v_pk_add_f32 v[90:91], v[94:95], v[90:91]
	v_cvt_f32_f16_sdwa v75, v75 dst_sel:DWORD dst_unused:UNUSED_PAD src0_sel:WORD_1
	v_add_f32_e32 v65, v90, v91
	v_cvt_f32_f16_e32 v88, v76
	v_cvt_f32_f16_sdwa v89, v76 dst_sel:DWORD dst_unused:UNUSED_PAD src0_sel:WORD_1
	v_add_f32_dpp v65, v65, v65 quad_perm:[1,0,3,2] row_mask:0xf bank_mask:0xf bound_ctrl:1
	v_cvt_f32_f16_e32 v76, v77
	v_cvt_f32_f16_sdwa v77, v77 dst_sel:DWORD dst_unused:UNUSED_PAD src0_sel:WORD_1
	v_add_f32_dpp v65, v65, v65 quad_perm:[2,3,0,1] row_mask:0xf bank_mask:0xf bound_ctrl:1
	s_nop 1
	v_add_f32_dpp v65, v65, v65 row_half_mirror row_mask:0xf bank_mask:0xf bound_ctrl:1
	v_fma_mix_f32 v91, v65, s42, v70 op_sel:[0,0,1] op_sel_hi:[0,0,1]
	v_fma_mix_f32 v90, v65, s42, v70 op_sel_hi:[0,0,1]
	v_fma_mix_f32 v93, v65, s42, v71 op_sel:[0,0,1] op_sel_hi:[0,0,1]
	v_fma_mix_f32 v92, v65, s42, v71 op_sel_hi:[0,0,1]
	v_fma_mix_f32 v71, v65, s42, v73 op_sel:[0,0,1] op_sel_hi:[0,0,1]
	v_fma_mix_f32 v70, v65, s42, v73 op_sel_hi:[0,0,1]
	v_fma_mix_f32 v73, v65, s42, v72 op_sel:[0,0,1] op_sel_hi:[0,0,1]
	v_fma_mix_f32 v72, v65, s42, v72 op_sel_hi:[0,0,1]
	v_pk_mul_f32 v[94:95], v[72:73], v[72:73]
	v_pk_mul_f32 v[96:97], v[70:71], v[70:71]
	v_pk_fma_f32 v[94:95], v[90:91], v[90:91], v[94:95]
	v_pk_fma_f32 v[96:97], v[92:93], v[92:93], v[96:97]
	s_nop 0
	v_pk_mov_b32 v[98:99], v[94:95], v[96:97] op_sel:[1,0]
	v_mov_b32_e32 v95, v97
	v_pk_add_f32 v[94:95], v[98:99], v[94:95]
	s_nop 0
	v_add_f32_e32 v65, v94, v95
	s_nop 1
	v_add_f32_dpp v65, v65, v65 quad_perm:[1,0,3,2] row_mask:0xf bank_mask:0xf bound_ctrl:1
	s_nop 1
	v_add_f32_dpp v65, v65, v65 quad_perm:[2,3,0,1] row_mask:0xf bank_mask:0xf bound_ctrl:1
	s_nop 1
	v_add_f32_dpp v65, v65, v65 row_half_mirror row_mask:0xf bank_mask:0xf bound_ctrl:1
	v_fmamk_f32 v65, v65, 0x3c800000, v63
	v_mul_f32_e32 v79, 0x4b800000, v65
	v_cmp_gt_f32_e32 vcc, s43, v65
	s_nop 1
	v_cndmask_b32_e32 v65, v65, v79, vcc
	v_rsq_f32_e32 v65, v65
	s_nop 0
	v_mul_f32_e32 v79, 0x45800000, v65
	v_cndmask_b32_e32 v94, v65, v79, vcc
	v_pk_mul_f32 v[90:91], v[90:91], v[94:95] op_sel_hi:[1,0]
	v_pk_mul_f32 v[92:93], v[92:93], v[94:95] op_sel_hi:[1,0]
	v_pk_mul_f32 v[72:73], v[72:73], v[94:95] op_sel_hi:[1,0]
	v_pk_mul_f32 v[70:71], v[70:71], v[94:95] op_sel_hi:[1,0]
	v_pk_fma_f32 v[92:93], v[6:7], v[92:93], v[14:15]
	v_pk_fma_f32 v[90:91], v[4:5], v[90:91], v[12:13]
	v_pk_fma_f32 v[70:71], v[2:3], v[70:71], v[10:11]
	v_pk_fma_f32 v[72:73], v[0:1], v[72:73], v[8:9]
	v_pk_fma_f32 v[68:69], v[78:79], v[68:69], v[90:91] op_sel_hi:[0,1,1]
	v_pk_fma_f32 v[74:75], v[78:79], v[74:75], v[92:93] op_sel_hi:[0,1,1]
	v_pk_fma_f32 v[72:73], v[78:79], v[88:89], v[72:73] op_sel_hi:[0,1,1]
	v_pk_fma_f32 v[70:71], v[78:79], v[76:77], v[70:71] op_sel_hi:[0,1,1]
	v_pk_mul_f32 v[74:75], v[84:85], v[74:75]
	v_pk_mul_f32 v[76:77], v[80:81], v[68:69]
	v_pk_mul_f32 v[68:69], v[86:87], v[70:71]
	v_pk_mul_f32 v[66:67], v[66:67], v[72:73]
	v_cvt_pk_f16_f32 v69, v68, v69
	v_cvt_pk_f16_f32 v68, v66, v67
	v_cvt_pk_f16_f32 v67, v74, v75
	v_cvt_pk_f16_f32 v66, v76, v77
	global_store_dwordx4 v[82:83], v[66:69], off
	s_movk_i32 s45, 0x80
	s_add_i32 s44, s44, s84
	s_cmpk_gt_i32 s44, 0x427
	v_add_u32_e32 v42, s34, v42
	s_barrier
	s_cbranch_scc0 .LBB0_709
	v_readlane_b32 s50, v238, 40
	v_readlane_b32 s51, v238, 41

.LBB0_1079:
	v_or_b32_e32 v6, s12, v128
	v_ashrrev_i32_e32 v1, 31, v0
	v_ashrrev_i32_e32 v7, 31, v6
	v_lshlrev_b64 v[4:5], 11, v[0:1]
	v_lshl_add_u64 v[6:7], v[6:7], 1, s[50:51]
	s_mov_b64 s[12:13], 0x8000
	v_lshl_add_u64 v[8:9], v[2:3], 0, v[4:5]
	v_lshl_add_u64 v[24:25], v[6:7], 0, v[4:5]
	global_load_dwordx4 v[40:43], v[8:9], off
	v_lshl_add_u64 v[10:11], v[8:9], 0, s[12:13]
	global_load_dwordx4 v[44:47], v[10:11], off
	v_lshl_add_u64 v[12:13], v[10:11], 0, s[12:13]
	global_load_dwordx4 v[48:51], v[12:13], off
	v_lshl_add_u64 v[14:15], v[12:13], 0, s[12:13]
	global_load_dwordx4 v[52:55], v[14:15], off
	v_lshl_add_u64 v[16:17], v[14:15], 0, s[12:13]
	global_load_dwordx4 v[56:59], v[16:17], off
	v_lshl_add_u64 v[18:19], v[16:17], 0, s[12:13]
	global_load_dwordx4 v[60:63], v[18:19], off
	v_lshl_add_u64 v[20:21], v[18:19], 0, s[12:13]
	global_load_dwordx4 v[64:67], v[20:21], off
	v_lshl_add_u64 v[22:23], v[20:21], 0, s[12:13]
	global_load_dwordx4 v[68:71], v[22:23], off
	global_load_dwordx4 v[72:75], v[24:25], off
	v_lshl_add_u64 v[26:27], v[24:25], 0, s[12:13]
	global_load_dwordx4 v[76:79], v[26:27], off
	v_lshl_add_u64 v[28:29], v[26:27], 0, s[12:13]
	global_load_dwordx4 v[80:83], v[28:29], off
	v_lshl_add_u64 v[30:31], v[28:29], 0, s[12:13]
	global_load_dwordx4 v[84:87], v[30:31], off
	v_lshl_add_u64 v[32:33], v[30:31], 0, s[12:13]
	global_load_dwordx4 v[88:91], v[32:33], off
	v_lshl_add_u64 v[34:35], v[32:33], 0, s[12:13]
	global_load_dwordx4 v[92:95], v[34:35], off
	v_lshl_add_u64 v[36:37], v[34:35], 0, s[12:13]
	global_load_dwordx4 v[96:99], v[36:37], off
	v_lshl_add_u64 v[38:39], v[36:37], 0, s[12:13]
	global_load_dwordx4 v[100:103], v[38:39], off
	ds_read_b128 v[104:107], v172
	ds_read_b128 v[108:111], v172 offset:4096
	s_waitcnt lgkmcnt(1)
	v_cvt_f32_f16_e32 v112, v104
	v_cvt_f32_f16_sdwa v113, v104 dst_sel:DWORD dst_unused:UNUSED_PAD src0_sel:WORD_1
	v_cvt_f32_f16_e32 v114, v105
	v_cvt_f32_f16_sdwa v115, v105 dst_sel:DWORD dst_unused:UNUSED_PAD src0_sel:WORD_1
	v_cvt_f32_f16_e32 v116, v106
	v_cvt_f32_f16_sdwa v117, v106 dst_sel:DWORD dst_unused:UNUSED_PAD src0_sel:WORD_1
	v_cvt_f32_f16_e32 v118, v107
	v_cvt_f32_f16_sdwa v119, v107 dst_sel:DWORD dst_unused:UNUSED_PAD src0_sel:WORD_1
	s_waitcnt vmcnt(15)
	v_cvt_f32_f16_e32 v240, v40
	v_cvt_f32_f16_sdwa v241, v40 dst_sel:DWORD dst_unused:UNUSED_PAD src0_sel:WORD_1
	v_cvt_f32_f16_e32 v242, v41
	v_cvt_f32_f16_sdwa v243, v41 dst_sel:DWORD dst_unused:UNUSED_PAD src0_sel:WORD_1
	v_cvt_f32_f16_e32 v244, v42
	v_cvt_f32_f16_sdwa v245, v42 dst_sel:DWORD dst_unused:UNUSED_PAD src0_sel:WORD_1
	v_cvt_f32_f16_e32 v246, v43
	v_cvt_f32_f16_sdwa v247, v43 dst_sel:DWORD dst_unused:UNUSED_PAD src0_sel:WORD_1
	v_pk_add_f32 v[112:113], v[112:113], v[240:241]
	v_pk_add_f32 v[114:115], v[114:115], v[242:243]
	v_pk_add_f32 v[116:117], v[116:117], v[244:245]
	v_pk_add_f32 v[118:119], v[118:119], v[246:247]
	v_cvt_pk_f16_f32 v40, v112, v113
	v_cvt_pk_f16_f32 v41, v114, v115
	v_cvt_pk_f16_f32 v42, v116, v117
	v_cvt_pk_f16_f32 v43, v118, v119
	global_store_dwordx4 v[8:9], v[40:43], off
	ds_read_b128 v[104:107], v172 offset:8192
	s_waitcnt lgkmcnt(1)
	v_cvt_f32_f16_e32 v112, v108
	v_cvt_f32_f16_sdwa v113, v108 dst_sel:DWORD dst_unused:UNUSED_PAD src0_sel:WORD_1
	v_cvt_f32_f16_e32 v114, v109
	v_cvt_f32_f16_sdwa v115, v109 dst_sel:DWORD dst_unused:UNUSED_PAD src0_sel:WORD_1
	v_cvt_f32_f16_e32 v116, v110
	v_cvt_f32_f16_sdwa v117, v110 dst_sel:DWORD dst_unused:UNUSED_PAD src0_sel:WORD_1
	v_cvt_f32_f16_e32 v118, v111
	v_cvt_f32_f16_sdwa v119, v111 dst_sel:DWORD dst_unused:UNUSED_PAD src0_sel:WORD_1
	s_waitcnt vmcnt(14)
	v_cvt_f32_f16_e32 v240, v44
	v_cvt_f32_f16_sdwa v241, v44 dst_sel:DWORD dst_unused:UNUSED_PAD src0_sel:WORD_1
	v_cvt_f32_f16_e32 v242, v45
	v_cvt_f32_f16_sdwa v243, v45 dst_sel:DWORD dst_unused:UNUSED_PAD src0_sel:WORD_1
	v_cvt_f32_f16_e32 v244, v46
	v_cvt_f32_f16_sdwa v245, v46 dst_sel:DWORD dst_unused:UNUSED_PAD src0_sel:WORD_1
	v_cvt_f32_f16_e32 v246, v47
	v_cvt_f32_f16_sdwa v247, v47 dst_sel:DWORD dst_unused:UNUSED_PAD src0_sel:WORD_1
	v_pk_add_f32 v[112:113], v[112:113], v[240:241]
	v_pk_add_f32 v[114:115], v[114:115], v[242:243]
	v_pk_add_f32 v[116:117], v[116:117], v[244:245]
	v_pk_add_f32 v[118:119], v[118:119], v[246:247]
	v_cvt_pk_f16_f32 v44, v112, v113
	v_cvt_pk_f16_f32 v45, v114, v115
	v_cvt_pk_f16_f32 v46, v116, v117
	v_cvt_pk_f16_f32 v47, v118, v119
	global_store_dwordx4 v[10:11], v[44:47], off
	ds_read_b128 v[108:111], v172 offset:12288
	s_waitcnt lgkmcnt(1)
	v_cvt_f32_f16_e32 v112, v104
	v_cvt_f32_f16_sdwa v113, v104 dst_sel:DWORD dst_unused:UNUSED_PAD src0_sel:WORD_1
	v_cvt_f32_f16_e32 v114, v105
	v_cvt_f32_f16_sdwa v115, v105 dst_sel:DWORD dst_unused:UNUSED_PAD src0_sel:WORD_1
	v_cvt_f32_f16_e32 v116, v106
	v_cvt_f32_f16_sdwa v117, v106 dst_sel:DWORD dst_unused:UNUSED_PAD src0_sel:WORD_1
	v_cvt_f32_f16_e32 v118, v107
	v_cvt_f32_f16_sdwa v119, v107 dst_sel:DWORD dst_unused:UNUSED_PAD src0_sel:WORD_1
	s_waitcnt vmcnt(13)
	v_cvt_f32_f16_e32 v240, v48
	v_cvt_f32_f16_sdwa v241, v48 dst_sel:DWORD dst_unused:UNUSED_PAD src0_sel:WORD_1
	v_cvt_f32_f16_e32 v242, v49
	v_cvt_f32_f16_sdwa v243, v49 dst_sel:DWORD dst_unused:UNUSED_PAD src0_sel:WORD_1
	v_cvt_f32_f16_e32 v244, v50
	v_cvt_f32_f16_sdwa v245, v50 dst_sel:DWORD dst_unused:UNUSED_PAD src0_sel:WORD_1
	v_cvt_f32_f16_e32 v246, v51
	v_cvt_f32_f16_sdwa v247, v51 dst_sel:DWORD dst_unused:UNUSED_PAD src0_sel:WORD_1
	v_pk_add_f32 v[112:113], v[112:113], v[240:241]
	v_pk_add_f32 v[114:115], v[114:115], v[242:243]
	v_pk_add_f32 v[116:117], v[116:117], v[244:245]
	v_pk_add_f32 v[118:119], v[118:119], v[246:247]
	v_cvt_pk_f16_f32 v48, v112, v113
	v_cvt_pk_f16_f32 v49, v114, v115
	v_cvt_pk_f16_f32 v50, v116, v117
	v_cvt_pk_f16_f32 v51, v118, v119
	global_store_dwordx4 v[12:13], v[48:51], off
	ds_read_b128 v[104:107], v172 offset:16384
	s_waitcnt lgkmcnt(1)
	v_cvt_f32_f16_e32 v112, v108
	v_cvt_f32_f16_sdwa v113, v108 dst_sel:DWORD dst_unused:UNUSED_PAD src0_sel:WORD_1
	v_cvt_f32_f16_e32 v114, v109
	v_cvt_f32_f16_sdwa v115, v109 dst_sel:DWORD dst_unused:UNUSED_PAD src0_sel:WORD_1
	v_cvt_f32_f16_e32 v116, v110
	v_cvt_f32_f16_sdwa v117, v110 dst_sel:DWORD dst_unused:UNUSED_PAD src0_sel:WORD_1
	v_cvt_f32_f16_e32 v118, v111
	v_cvt_f32_f16_sdwa v119, v111 dst_sel:DWORD dst_unused:UNUSED_PAD src0_sel:WORD_1
	s_waitcnt vmcnt(12)
	v_cvt_f32_f16_e32 v240, v52
	v_cvt_f32_f16_sdwa v241, v52 dst_sel:DWORD dst_unused:UNUSED_PAD src0_sel:WORD_1
	v_cvt_f32_f16_e32 v242, v53
	v_cvt_f32_f16_sdwa v243, v53 dst_sel:DWORD dst_unused:UNUSED_PAD src0_sel:WORD_1
	v_cvt_f32_f16_e32 v244, v54
	v_cvt_f32_f16_sdwa v245, v54 dst_sel:DWORD dst_unused:UNUSED_PAD src0_sel:WORD_1
	v_cvt_f32_f16_e32 v246, v55
	v_cvt_f32_f16_sdwa v247, v55 dst_sel:DWORD dst_unused:UNUSED_PAD src0_sel:WORD_1
	v_pk_add_f32 v[112:113], v[112:113], v[240:241]
	v_pk_add_f32 v[114:115], v[114:115], v[242:243]
	v_pk_add_f32 v[116:117], v[116:117], v[244:245]
	v_pk_add_f32 v[118:119], v[118:119], v[246:247]
	v_cvt_pk_f16_f32 v52, v112, v113
	v_cvt_pk_f16_f32 v53, v114, v115
	v_cvt_pk_f16_f32 v54, v116, v117
	v_cvt_pk_f16_f32 v55, v118, v119
	global_store_dwordx4 v[14:15], v[52:55], off
	ds_read_b128 v[108:111], v172 offset:20480
	s_waitcnt lgkmcnt(1)
	v_cvt_f32_f16_e32 v112, v104
	v_cvt_f32_f16_sdwa v113, v104 dst_sel:DWORD dst_unused:UNUSED_PAD src0_sel:WORD_1
	v_cvt_f32_f16_e32 v114, v105
	v_cvt_f32_f16_sdwa v115, v105 dst_sel:DWORD dst_unused:UNUSED_PAD src0_sel:WORD_1
	v_cvt_f32_f16_e32 v116, v106
	v_cvt_f32_f16_sdwa v117, v106 dst_sel:DWORD dst_unused:UNUSED_PAD src0_sel:WORD_1
	v_cvt_f32_f16_e32 v118, v107
	v_cvt_f32_f16_sdwa v119, v107 dst_sel:DWORD dst_unused:UNUSED_PAD src0_sel:WORD_1
	s_waitcnt vmcnt(11)
	v_cvt_f32_f16_e32 v240, v56
	v_cvt_f32_f16_sdwa v241, v56 dst_sel:DWORD dst_unused:UNUSED_PAD src0_sel:WORD_1
	v_cvt_f32_f16_e32 v242, v57
	v_cvt_f32_f16_sdwa v243, v57 dst_sel:DWORD dst_unused:UNUSED_PAD src0_sel:WORD_1
	v_cvt_f32_f16_e32 v244, v58
	v_cvt_f32_f16_sdwa v245, v58 dst_sel:DWORD dst_unused:UNUSED_PAD src0_sel:WORD_1
	v_cvt_f32_f16_e32 v246, v59
	v_cvt_f32_f16_sdwa v247, v59 dst_sel:DWORD dst_unused:UNUSED_PAD src0_sel:WORD_1
	v_pk_add_f32 v[112:113], v[112:113], v[240:241]
	v_pk_add_f32 v[114:115], v[114:115], v[242:243]
	v_pk_add_f32 v[116:117], v[116:117], v[244:245]
	v_pk_add_f32 v[118:119], v[118:119], v[246:247]
	v_cvt_pk_f16_f32 v56, v112, v113
	v_cvt_pk_f16_f32 v57, v114, v115
	v_cvt_pk_f16_f32 v58, v116, v117
	v_cvt_pk_f16_f32 v59, v118, v119
	global_store_dwordx4 v[16:17], v[56:59], off
	ds_read_b128 v[104:107], v172 offset:24576
	s_waitcnt lgkmcnt(1)
	v_cvt_f32_f16_e32 v112, v108
	v_cvt_f32_f16_sdwa v113, v108 dst_sel:DWORD dst_unused:UNUSED_PAD src0_sel:WORD_1
	v_cvt_f32_f16_e32 v114, v109
	v_cvt_f32_f16_sdwa v115, v109 dst_sel:DWORD dst_unused:UNUSED_PAD src0_sel:WORD_1
	v_cvt_f32_f16_e32 v116, v110
	v_cvt_f32_f16_sdwa v117, v110 dst_sel:DWORD dst_unused:UNUSED_PAD src0_sel:WORD_1
	v_cvt_f32_f16_e32 v118, v111
	v_cvt_f32_f16_sdwa v119, v111 dst_sel:DWORD dst_unused:UNUSED_PAD src0_sel:WORD_1
	s_waitcnt vmcnt(10)
	v_cvt_f32_f16_e32 v240, v60
	v_cvt_f32_f16_sdwa v241, v60 dst_sel:DWORD dst_unused:UNUSED_PAD src0_sel:WORD_1
	v_cvt_f32_f16_e32 v242, v61
	v_cvt_f32_f16_sdwa v243, v61 dst_sel:DWORD dst_unused:UNUSED_PAD src0_sel:WORD_1
	v_cvt_f32_f16_e32 v244, v62
	v_cvt_f32_f16_sdwa v245, v62 dst_sel:DWORD dst_unused:UNUSED_PAD src0_sel:WORD_1
	v_cvt_f32_f16_e32 v246, v63
	v_cvt_f32_f16_sdwa v247, v63 dst_sel:DWORD dst_unused:UNUSED_PAD src0_sel:WORD_1
	v_pk_add_f32 v[112:113], v[112:113], v[240:241]
	v_pk_add_f32 v[114:115], v[114:115], v[242:243]
	v_pk_add_f32 v[116:117], v[116:117], v[244:245]
	v_pk_add_f32 v[118:119], v[118:119], v[246:247]
	v_cvt_pk_f16_f32 v60, v112, v113
	v_cvt_pk_f16_f32 v61, v114, v115
	v_cvt_pk_f16_f32 v62, v116, v117
	v_cvt_pk_f16_f32 v63, v118, v119
	global_store_dwordx4 v[18:19], v[60:63], off
	ds_read_b128 v[108:111], v172 offset:28672
	s_waitcnt lgkmcnt(1)
	v_cvt_f32_f16_e32 v112, v104
	v_cvt_f32_f16_sdwa v113, v104 dst_sel:DWORD dst_unused:UNUSED_PAD src0_sel:WORD_1
	v_cvt_f32_f16_e32 v114, v105
	v_cvt_f32_f16_sdwa v115, v105 dst_sel:DWORD dst_unused:UNUSED_PAD src0_sel:WORD_1
	v_cvt_f32_f16_e32 v116, v106
	v_cvt_f32_f16_sdwa v117, v106 dst_sel:DWORD dst_unused:UNUSED_PAD src0_sel:WORD_1
	v_cvt_f32_f16_e32 v118, v107
	v_cvt_f32_f16_sdwa v119, v107 dst_sel:DWORD dst_unused:UNUSED_PAD src0_sel:WORD_1
	s_waitcnt vmcnt(9)
	v_cvt_f32_f16_e32 v240, v64
	v_cvt_f32_f16_sdwa v241, v64 dst_sel:DWORD dst_unused:UNUSED_PAD src0_sel:WORD_1
	v_cvt_f32_f16_e32 v242, v65
	v_cvt_f32_f16_sdwa v243, v65 dst_sel:DWORD dst_unused:UNUSED_PAD src0_sel:WORD_1
	v_cvt_f32_f16_e32 v244, v66
	v_cvt_f32_f16_sdwa v245, v66 dst_sel:DWORD dst_unused:UNUSED_PAD src0_sel:WORD_1
	v_cvt_f32_f16_e32 v246, v67
	v_cvt_f32_f16_sdwa v247, v67 dst_sel:DWORD dst_unused:UNUSED_PAD src0_sel:WORD_1
	v_pk_add_f32 v[112:113], v[112:113], v[240:241]
	v_pk_add_f32 v[114:115], v[114:115], v[242:243]
	v_pk_add_f32 v[116:117], v[116:117], v[244:245]
	v_pk_add_f32 v[118:119], v[118:119], v[246:247]
	v_cvt_pk_f16_f32 v64, v112, v113
	v_cvt_pk_f16_f32 v65, v114, v115
	v_cvt_pk_f16_f32 v66, v116, v117
	v_cvt_pk_f16_f32 v67, v118, v119
	global_store_dwordx4 v[20:21], v[64:67], off
	ds_read_b128 v[104:107], v173
	s_waitcnt lgkmcnt(1)
	v_cvt_f32_f16_e32 v112, v108
	v_cvt_f32_f16_sdwa v113, v108 dst_sel:DWORD dst_unused:UNUSED_PAD src0_sel:WORD_1
	v_cvt_f32_f16_e32 v114, v109
	v_cvt_f32_f16_sdwa v115, v109 dst_sel:DWORD dst_unused:UNUSED_PAD src0_sel:WORD_1
	v_cvt_f32_f16_e32 v116, v110
	v_cvt_f32_f16_sdwa v117, v110 dst_sel:DWORD dst_unused:UNUSED_PAD src0_sel:WORD_1
	v_cvt_f32_f16_e32 v118, v111
	v_cvt_f32_f16_sdwa v119, v111 dst_sel:DWORD dst_unused:UNUSED_PAD src0_sel:WORD_1
	s_waitcnt vmcnt(8)
	v_cvt_f32_f16_e32 v240, v68
	v_cvt_f32_f16_sdwa v241, v68 dst_sel:DWORD dst_unused:UNUSED_PAD src0_sel:WORD_1
	v_cvt_f32_f16_e32 v242, v69
	v_cvt_f32_f16_sdwa v243, v69 dst_sel:DWORD dst_unused:UNUSED_PAD src0_sel:WORD_1
	v_cvt_f32_f16_e32 v244, v70
	v_cvt_f32_f16_sdwa v245, v70 dst_sel:DWORD dst_unused:UNUSED_PAD src0_sel:WORD_1
	v_cvt_f32_f16_e32 v246, v71
	v_cvt_f32_f16_sdwa v247, v71 dst_sel:DWORD dst_unused:UNUSED_PAD src0_sel:WORD_1
	v_pk_add_f32 v[112:113], v[112:113], v[240:241]
	v_pk_add_f32 v[114:115], v[114:115], v[242:243]
	v_pk_add_f32 v[116:117], v[116:117], v[244:245]
	v_pk_add_f32 v[118:119], v[118:119], v[246:247]
	v_cvt_pk_f16_f32 v68, v112, v113
	v_cvt_pk_f16_f32 v69, v114, v115
	v_cvt_pk_f16_f32 v70, v116, v117
	v_cvt_pk_f16_f32 v71, v118, v119
	global_store_dwordx4 v[22:23], v[68:71], off
	ds_read_b128 v[108:111], v173 offset:4096
	s_waitcnt lgkmcnt(1)
	v_cvt_f32_f16_e32 v112, v104
	v_cvt_f32_f16_sdwa v113, v104 dst_sel:DWORD dst_unused:UNUSED_PAD src0_sel:WORD_1
	v_cvt_f32_f16_e32 v114, v105
	v_cvt_f32_f16_sdwa v115, v105 dst_sel:DWORD dst_unused:UNUSED_PAD src0_sel:WORD_1
	v_cvt_f32_f16_e32 v116, v106
	v_cvt_f32_f16_sdwa v117, v106 dst_sel:DWORD dst_unused:UNUSED_PAD src0_sel:WORD_1
	v_cvt_f32_f16_e32 v118, v107
	v_cvt_f32_f16_sdwa v119, v107 dst_sel:DWORD dst_unused:UNUSED_PAD src0_sel:WORD_1
	s_waitcnt vmcnt(7)
	v_cvt_f32_f16_e32 v240, v72
	v_cvt_f32_f16_sdwa v241, v72 dst_sel:DWORD dst_unused:UNUSED_PAD src0_sel:WORD_1
	v_cvt_f32_f16_e32 v242, v73
	v_cvt_f32_f16_sdwa v243, v73 dst_sel:DWORD dst_unused:UNUSED_PAD src0_sel:WORD_1
	v_cvt_f32_f16_e32 v244, v74
	v_cvt_f32_f16_sdwa v245, v74 dst_sel:DWORD dst_unused:UNUSED_PAD src0_sel:WORD_1
	v_cvt_f32_f16_e32 v246, v75
	v_cvt_f32_f16_sdwa v247, v75 dst_sel:DWORD dst_unused:UNUSED_PAD src0_sel:WORD_1
	v_pk_add_f32 v[112:113], v[112:113], v[240:241]
	v_pk_add_f32 v[114:115], v[114:115], v[242:243]
	v_pk_add_f32 v[116:117], v[116:117], v[244:245]
	v_pk_add_f32 v[118:119], v[118:119], v[246:247]
	v_cvt_pk_f16_f32 v72, v112, v113
	v_cvt_pk_f16_f32 v73, v114, v115
	v_cvt_pk_f16_f32 v74, v116, v117
	v_cvt_pk_f16_f32 v75, v118, v119
	global_store_dwordx4 v[24:25], v[72:75], off
	ds_read_b128 v[104:107], v173 offset:8192
	s_waitcnt lgkmcnt(1)
	v_cvt_f32_f16_e32 v112, v108
	v_cvt_f32_f16_sdwa v113, v108 dst_sel:DWORD dst_unused:UNUSED_PAD src0_sel:WORD_1
	v_cvt_f32_f16_e32 v114, v109
	v_cvt_f32_f16_sdwa v115, v109 dst_sel:DWORD dst_unused:UNUSED_PAD src0_sel:WORD_1
	v_cvt_f32_f16_e32 v116, v110
	v_cvt_f32_f16_sdwa v117, v110 dst_sel:DWORD dst_unused:UNUSED_PAD src0_sel:WORD_1
	v_cvt_f32_f16_e32 v118, v111
	v_cvt_f32_f16_sdwa v119, v111 dst_sel:DWORD dst_unused:UNUSED_PAD src0_sel:WORD_1
	s_waitcnt vmcnt(6)
	v_cvt_f32_f16_e32 v240, v76
	v_cvt_f32_f16_sdwa v241, v76 dst_sel:DWORD dst_unused:UNUSED_PAD src0_sel:WORD_1
	v_cvt_f32_f16_e32 v242, v77
	v_cvt_f32_f16_sdwa v243, v77 dst_sel:DWORD dst_unused:UNUSED_PAD src0_sel:WORD_1
	v_cvt_f32_f16_e32 v244, v78
	v_cvt_f32_f16_sdwa v245, v78 dst_sel:DWORD dst_unused:UNUSED_PAD src0_sel:WORD_1
	v_cvt_f32_f16_e32 v246, v79
	v_cvt_f32_f16_sdwa v247, v79 dst_sel:DWORD dst_unused:UNUSED_PAD src0_sel:WORD_1
	v_pk_add_f32 v[112:113], v[112:113], v[240:241]
	v_pk_add_f32 v[114:115], v[114:115], v[242:243]
	v_pk_add_f32 v[116:117], v[116:117], v[244:245]
	v_pk_add_f32 v[118:119], v[118:119], v[246:247]
	v_cvt_pk_f16_f32 v76, v112, v113
	v_cvt_pk_f16_f32 v77, v114, v115
	v_cvt_pk_f16_f32 v78, v116, v117
	v_cvt_pk_f16_f32 v79, v118, v119
	global_store_dwordx4 v[26:27], v[76:79], off
	ds_read_b128 v[108:111], v173 offset:12288
	s_waitcnt lgkmcnt(1)
	v_cvt_f32_f16_e32 v112, v104
	v_cvt_f32_f16_sdwa v113, v104 dst_sel:DWORD dst_unused:UNUSED_PAD src0_sel:WORD_1
	v_cvt_f32_f16_e32 v114, v105
	v_cvt_f32_f16_sdwa v115, v105 dst_sel:DWORD dst_unused:UNUSED_PAD src0_sel:WORD_1
	v_cvt_f32_f16_e32 v116, v106
	v_cvt_f32_f16_sdwa v117, v106 dst_sel:DWORD dst_unused:UNUSED_PAD src0_sel:WORD_1
	v_cvt_f32_f16_e32 v118, v107
	v_cvt_f32_f16_sdwa v119, v107 dst_sel:DWORD dst_unused:UNUSED_PAD src0_sel:WORD_1
	s_waitcnt vmcnt(5)
	v_cvt_f32_f16_e32 v240, v80
	v_cvt_f32_f16_sdwa v241, v80 dst_sel:DWORD dst_unused:UNUSED_PAD src0_sel:WORD_1
	v_cvt_f32_f16_e32 v242, v81
	v_cvt_f32_f16_sdwa v243, v81 dst_sel:DWORD dst_unused:UNUSED_PAD src0_sel:WORD_1
	v_cvt_f32_f16_e32 v244, v82
	v_cvt_f32_f16_sdwa v245, v82 dst_sel:DWORD dst_unused:UNUSED_PAD src0_sel:WORD_1
	v_cvt_f32_f16_e32 v246, v83
	v_cvt_f32_f16_sdwa v247, v83 dst_sel:DWORD dst_unused:UNUSED_PAD src0_sel:WORD_1
	v_pk_add_f32 v[112:113], v[112:113], v[240:241]
	v_pk_add_f32 v[114:115], v[114:115], v[242:243]
	v_pk_add_f32 v[116:117], v[116:117], v[244:245]
	v_pk_add_f32 v[118:119], v[118:119], v[246:247]
	v_cvt_pk_f16_f32 v80, v112, v113
	v_cvt_pk_f16_f32 v81, v114, v115
	v_cvt_pk_f16_f32 v82, v116, v117
	v_cvt_pk_f16_f32 v83, v118, v119
	global_store_dwordx4 v[28:29], v[80:83], off
	ds_read_b128 v[104:107], v173 offset:16384
	s_waitcnt lgkmcnt(1)
	v_cvt_f32_f16_e32 v112, v108
	v_cvt_f32_f16_sdwa v113, v108 dst_sel:DWORD dst_unused:UNUSED_PAD src0_sel:WORD_1
	v_cvt_f32_f16_e32 v114, v109
	v_cvt_f32_f16_sdwa v115, v109 dst_sel:DWORD dst_unused:UNUSED_PAD src0_sel:WORD_1
	v_cvt_f32_f16_e32 v116, v110
	v_cvt_f32_f16_sdwa v117, v110 dst_sel:DWORD dst_unused:UNUSED_PAD src0_sel:WORD_1
	v_cvt_f32_f16_e32 v118, v111
	v_cvt_f32_f16_sdwa v119, v111 dst_sel:DWORD dst_unused:UNUSED_PAD src0_sel:WORD_1
	s_waitcnt vmcnt(4)
	v_cvt_f32_f16_e32 v240, v84
	v_cvt_f32_f16_sdwa v241, v84 dst_sel:DWORD dst_unused:UNUSED_PAD src0_sel:WORD_1
	v_cvt_f32_f16_e32 v242, v85
	v_cvt_f32_f16_sdwa v243, v85 dst_sel:DWORD dst_unused:UNUSED_PAD src0_sel:WORD_1
	v_cvt_f32_f16_e32 v244, v86
	v_cvt_f32_f16_sdwa v245, v86 dst_sel:DWORD dst_unused:UNUSED_PAD src0_sel:WORD_1
	v_cvt_f32_f16_e32 v246, v87
	v_cvt_f32_f16_sdwa v247, v87 dst_sel:DWORD dst_unused:UNUSED_PAD src0_sel:WORD_1
	v_pk_add_f32 v[112:113], v[112:113], v[240:241]
	v_pk_add_f32 v[114:115], v[114:115], v[242:243]
	v_pk_add_f32 v[116:117], v[116:117], v[244:245]
	v_pk_add_f32 v[118:119], v[118:119], v[246:247]
	v_cvt_pk_f16_f32 v84, v112, v113
	v_cvt_pk_f16_f32 v85, v114, v115
	v_cvt_pk_f16_f32 v86, v116, v117
	v_cvt_pk_f16_f32 v87, v118, v119
	global_store_dwordx4 v[30:31], v[84:87], off
	ds_read_b128 v[108:111], v173 offset:20480
	s_waitcnt lgkmcnt(1)
	v_cvt_f32_f16_e32 v112, v104
	v_cvt_f32_f16_sdwa v113, v104 dst_sel:DWORD dst_unused:UNUSED_PAD src0_sel:WORD_1
	v_cvt_f32_f16_e32 v114, v105
	v_cvt_f32_f16_sdwa v115, v105 dst_sel:DWORD dst_unused:UNUSED_PAD src0_sel:WORD_1
	v_cvt_f32_f16_e32 v116, v106
	v_cvt_f32_f16_sdwa v117, v106 dst_sel:DWORD dst_unused:UNUSED_PAD src0_sel:WORD_1
	v_cvt_f32_f16_e32 v118, v107
	v_cvt_f32_f16_sdwa v119, v107 dst_sel:DWORD dst_unused:UNUSED_PAD src0_sel:WORD_1
	s_waitcnt vmcnt(3)
	v_cvt_f32_f16_e32 v240, v88
	v_cvt_f32_f16_sdwa v241, v88 dst_sel:DWORD dst_unused:UNUSED_PAD src0_sel:WORD_1
	v_cvt_f32_f16_e32 v242, v89
	v_cvt_f32_f16_sdwa v243, v89 dst_sel:DWORD dst_unused:UNUSED_PAD src0_sel:WORD_1
	v_cvt_f32_f16_e32 v244, v90
	v_cvt_f32_f16_sdwa v245, v90 dst_sel:DWORD dst_unused:UNUSED_PAD src0_sel:WORD_1
	v_cvt_f32_f16_e32 v246, v91
	v_cvt_f32_f16_sdwa v247, v91 dst_sel:DWORD dst_unused:UNUSED_PAD src0_sel:WORD_1
	v_pk_add_f32 v[112:113], v[112:113], v[240:241]
	v_pk_add_f32 v[114:115], v[114:115], v[242:243]
	v_pk_add_f32 v[116:117], v[116:117], v[244:245]
	v_pk_add_f32 v[118:119], v[118:119], v[246:247]
	v_cvt_pk_f16_f32 v88, v112, v113
	v_cvt_pk_f16_f32 v89, v114, v115
	v_cvt_pk_f16_f32 v90, v116, v117
	v_cvt_pk_f16_f32 v91, v118, v119
	global_store_dwordx4 v[32:33], v[88:91], off
	ds_read_b128 v[104:107], v173 offset:24576
	s_waitcnt lgkmcnt(1)
	v_cvt_f32_f16_e32 v112, v108
	v_cvt_f32_f16_sdwa v113, v108 dst_sel:DWORD dst_unused:UNUSED_PAD src0_sel:WORD_1
	v_cvt_f32_f16_e32 v114, v109
	v_cvt_f32_f16_sdwa v115, v109 dst_sel:DWORD dst_unused:UNUSED_PAD src0_sel:WORD_1
	v_cvt_f32_f16_e32 v116, v110
	v_cvt_f32_f16_sdwa v117, v110 dst_sel:DWORD dst_unused:UNUSED_PAD src0_sel:WORD_1
	v_cvt_f32_f16_e32 v118, v111
	v_cvt_f32_f16_sdwa v119, v111 dst_sel:DWORD dst_unused:UNUSED_PAD src0_sel:WORD_1
	s_waitcnt vmcnt(2)
	v_cvt_f32_f16_e32 v240, v92
	v_cvt_f32_f16_sdwa v241, v92 dst_sel:DWORD dst_unused:UNUSED_PAD src0_sel:WORD_1
	v_cvt_f32_f16_e32 v242, v93
	v_cvt_f32_f16_sdwa v243, v93 dst_sel:DWORD dst_unused:UNUSED_PAD src0_sel:WORD_1
	v_cvt_f32_f16_e32 v244, v94
	v_cvt_f32_f16_sdwa v245, v94 dst_sel:DWORD dst_unused:UNUSED_PAD src0_sel:WORD_1
	v_cvt_f32_f16_e32 v246, v95
	v_cvt_f32_f16_sdwa v247, v95 dst_sel:DWORD dst_unused:UNUSED_PAD src0_sel:WORD_1
	v_pk_add_f32 v[112:113], v[112:113], v[240:241]
	v_pk_add_f32 v[114:115], v[114:115], v[242:243]
	v_pk_add_f32 v[116:117], v[116:117], v[244:245]
	v_pk_add_f32 v[118:119], v[118:119], v[246:247]
	v_cvt_pk_f16_f32 v92, v112, v113
	v_cvt_pk_f16_f32 v93, v114, v115
	v_cvt_pk_f16_f32 v94, v116, v117
	v_cvt_pk_f16_f32 v95, v118, v119
	global_store_dwordx4 v[34:35], v[92:95], off
	ds_read_b128 v[108:111], v173 offset:28672
	s_waitcnt lgkmcnt(1)
	v_cvt_f32_f16_e32 v112, v104
	v_cvt_f32_f16_sdwa v113, v104 dst_sel:DWORD dst_unused:UNUSED_PAD src0_sel:WORD_1
	v_cvt_f32_f16_e32 v114, v105
	v_cvt_f32_f16_sdwa v115, v105 dst_sel:DWORD dst_unused:UNUSED_PAD src0_sel:WORD_1
	v_cvt_f32_f16_e32 v116, v106
	v_cvt_f32_f16_sdwa v117, v106 dst_sel:DWORD dst_unused:UNUSED_PAD src0_sel:WORD_1
	v_cvt_f32_f16_e32 v118, v107
	v_cvt_f32_f16_sdwa v119, v107 dst_sel:DWORD dst_unused:UNUSED_PAD src0_sel:WORD_1
	s_waitcnt vmcnt(1)
	v_cvt_f32_f16_e32 v240, v96
	v_cvt_f32_f16_sdwa v241, v96 dst_sel:DWORD dst_unused:UNUSED_PAD src0_sel:WORD_1
	v_cvt_f32_f16_e32 v242, v97
	v_cvt_f32_f16_sdwa v243, v97 dst_sel:DWORD dst_unused:UNUSED_PAD src0_sel:WORD_1
	v_cvt_f32_f16_e32 v244, v98
	v_cvt_f32_f16_sdwa v245, v98 dst_sel:DWORD dst_unused:UNUSED_PAD src0_sel:WORD_1
	v_cvt_f32_f16_e32 v246, v99
	v_cvt_f32_f16_sdwa v247, v99 dst_sel:DWORD dst_unused:UNUSED_PAD src0_sel:WORD_1
	v_pk_add_f32 v[112:113], v[112:113], v[240:241]
	v_pk_add_f32 v[114:115], v[114:115], v[242:243]
	v_pk_add_f32 v[116:117], v[116:117], v[244:245]
	v_pk_add_f32 v[118:119], v[118:119], v[246:247]
	v_cvt_pk_f16_f32 v96, v112, v113
	v_cvt_pk_f16_f32 v97, v114, v115
	v_cvt_pk_f16_f32 v98, v116, v117
	v_cvt_pk_f16_f32 v99, v118, v119
	global_store_dwordx4 v[36:37], v[96:99], off
	s_waitcnt lgkmcnt(0)
	v_cvt_f32_f16_e32 v112, v108
	v_cvt_f32_f16_sdwa v113, v108 dst_sel:DWORD dst_unused:UNUSED_PAD src0_sel:WORD_1
	v_cvt_f32_f16_e32 v114, v109
	v_cvt_f32_f16_sdwa v115, v109 dst_sel:DWORD dst_unused:UNUSED_PAD src0_sel:WORD_1
	v_cvt_f32_f16_e32 v116, v110
	v_cvt_f32_f16_sdwa v117, v110 dst_sel:DWORD dst_unused:UNUSED_PAD src0_sel:WORD_1
	v_cvt_f32_f16_e32 v118, v111
	v_cvt_f32_f16_sdwa v119, v111 dst_sel:DWORD dst_unused:UNUSED_PAD src0_sel:WORD_1
	s_waitcnt vmcnt(0)
	v_cvt_f32_f16_e32 v240, v100
	v_cvt_f32_f16_sdwa v241, v100 dst_sel:DWORD dst_unused:UNUSED_PAD src0_sel:WORD_1
	v_cvt_f32_f16_e32 v242, v101
	v_cvt_f32_f16_sdwa v243, v101 dst_sel:DWORD dst_unused:UNUSED_PAD src0_sel:WORD_1
	v_cvt_f32_f16_e32 v244, v102
	v_cvt_f32_f16_sdwa v245, v102 dst_sel:DWORD dst_unused:UNUSED_PAD src0_sel:WORD_1
	v_cvt_f32_f16_e32 v246, v103
	v_cvt_f32_f16_sdwa v247, v103 dst_sel:DWORD dst_unused:UNUSED_PAD src0_sel:WORD_1
	v_pk_add_f32 v[112:113], v[112:113], v[240:241]
	v_pk_add_f32 v[114:115], v[114:115], v[242:243]
	v_pk_add_f32 v[116:117], v[116:117], v[244:245]
	v_pk_add_f32 v[118:119], v[118:119], v[246:247]
	v_cvt_pk_f16_f32 v100, v112, v113
	v_cvt_pk_f16_f32 v101, v114, v115
	v_cvt_pk_f16_f32 v102, v116, v117
	v_cvt_pk_f16_f32 v103, v118, v119
	global_store_dwordx4 v[38:39], v[100:103], off
	s_add_i32 s11, s11, s84
	s_cmp_ge_i32 s11, s74
	v_add_u32_e32 v165, s10, v165
	s_barrier
	s_cbranch_scc0 .LBB0_1076
